# attention epilogue reads norm gain from an LDS-staged table; S1/S3 tile loads de-serialized (batched global loads, single wait, then LDS writes)
# speedup vs baseline: 1.1397x; 1.0165x over previous
.LBB0_504:
	s_cmpk_lt_i32 s24, 0x300
	s_cselect_b64 s[38:39], -1, 0
	s_and_b64 s[0:1], s[38:39], exec
	s_cselect_b32 s25, 0, 0xfffffd00
	s_add_i32 s25, s25, s24
	s_lshl_b32 s0, s25, 4
	s_and_b32 s18, s24, 3
	s_and_b32 s10, s0, 0xffffffc0
	s_cmpk_gt_i32 s24, 0x2ff
	s_mov_b64 s[0:1], -1
	s_mul_i32 s19, s18, 0x300000
	s_cbranch_scc0 .LBB0_508
	s_ashr_i32 s11, s10, 31
	s_mul_i32 s1, s10, 0x1c00
	s_mul_hi_i32 s0, s10, 0x1c00
	s_add_u32 s1, s62, s1
	s_addc_u32 s6, s63, s0
	s_lshl_b32 s0, s18, 8
	s_add_u32 s0, s1, s0
	v_mov_b32_e32 v155, v151
	s_addc_u32 s1, s6, 0
	v_lshl_add_u64 v[4:5], s[0:1], 0, v[154:155]
	s_mov_b64 s[0:1], 0x1000
	v_lshl_add_u64 v[6:7], v[4:5], 0, s[0:1]
	v_mov_b32_e32 v131, v151
	v_lshl_add_u64 v[64:65], v[6:7], 0, v[130:131]
	global_load_dwordx4 v[64:67], v[64:65], off
	v_mov_b32_e32 v133, v151
	v_mov_b32_e32 v135, v151
	v_mov_b32_e32 v137, v151
	s_mov_b64 s[0:1], 0x1400
	v_lshl_add_u64 v[4:5], v[4:5], 0, s[0:1]
	v_readlane_b32 s40, v250, 28
	v_readlane_b32 s41, v250, 29
	v_readlane_b32 s42, v250, 30
	v_readlane_b32 s43, v250, 31
	v_readlane_b32 s44, v250, 32
	v_readlane_b32 s45, v250, 33
	v_readlane_b32 s46, v250, 34
	v_readlane_b32 s47, v250, 35
	v_readlane_b32 s48, v250, 36
	v_readlane_b32 s49, v250, 37
	v_readlane_b32 s50, v250, 38
	v_readlane_b32 s51, v250, 39
	v_readlane_b32 s52, v250, 40
	v_readlane_b32 s53, v250, 41
	v_readlane_b32 s54, v250, 42
	v_readlane_b32 s55, v250, 43
	v_lshl_add_u64 v[68:69], v[6:7], 0, v[132:133]
	global_load_dwordx4 v[68:71], v[68:69], off
	v_lshl_add_u64 v[72:73], v[6:7], 0, v[134:135]
	global_load_dwordx4 v[72:75], v[72:73], off
	v_lshl_add_u64 v[76:77], v[6:7], 0, v[136:137]
	global_load_dwordx4 v[76:79], v[76:77], off
	v_lshl_add_u64 v[80:81], v[4:5], 0, v[130:131]
	global_load_dwordx4 v[80:83], v[80:81], off
	v_lshl_add_u64 v[84:85], v[4:5], 0, v[132:133]
	global_load_dwordx4 v[84:87], v[84:85], off
	v_lshl_add_u64 v[88:89], v[4:5], 0, v[134:135]
	global_load_dwordx4 v[88:91], v[88:89], off
	v_lshl_add_u64 v[92:93], v[4:5], 0, v[136:137]
	global_load_dwordx4 v[92:95], v[92:93], off
	s_waitcnt vmcnt(0)
	ds_write_b128 v170, v[64:67]
	ds_write_b128 v171, v[68:71]
	ds_write_b128 v172, v[72:75]
	ds_write_b128 v173, v[76:79]
	ds_write_b128 v179, v[80:83]
	ds_write_b128 v180, v[84:87]
	ds_write_b128 v181, v[88:91]
	ds_write_b128 v198, v[92:95]
	v_lshl_or_b32 v0, s18, 9, v158
	s_waitcnt lgkmcnt(0)
	s_barrier
	global_load_dword v1, v0, s[40:41] offset:2048
	s_nop 0
	global_load_dword v0, v0, s[40:41]
	s_waitcnt vmcnt(0)
	v_sub_f32_e32 v0, v1, v0
	v_mul_f32_e32 v1, 0x3fb8aa3b, v0
	v_fma_f32 v2, v0, s8, -v1
	v_rndne_f32_e32 v3, v1
	v_fmac_f32_e32 v2, 0x32a5705f, v0
	v_sub_f32_e32 v1, v1, v3
	v_add_f32_e32 v1, v1, v2
	v_exp_f32_e32 v1, v1
	v_cvt_i32_f32_e32 v2, v3
	v_cmp_ngt_f32_e32 vcc, s9, v0
	v_ldexp_f32 v1, v1, v2
	s_nop 0
	v_cndmask_b32_e32 v1, 0, v1, vcc
	v_cmp_nlt_f32_e32 vcc, s12, v0
	v_mov_b32_e32 v2, 1.0
	s_nop 0
	v_cndmask_b32_e32 v0, v225, v1, vcc
	v_add_f32_e32 v0, 1.0, v0
	v_div_scale_f32 v1, s[0:1], v0, v0, 1.0
	v_rcp_f32_e32 v3, v1
	s_mov_b32 s0, 0
	s_mov_b32 s1, 62
	v_fma_f32 v4, -v1, v3, 1.0
	v_fmac_f32_e32 v3, v4, v3
	v_div_scale_f32 v4, vcc, 1.0, v0, 1.0
	v_mul_f32_e32 v5, v4, v3
	v_fma_f32 v6, -v1, v5, v4
	v_fmac_f32_e32 v5, v6, v3
	v_fma_f32 v1, -v1, v5, v4
	v_div_fmas_f32 v1, v1, v3, v5
	v_div_fixup_f32 v0, v1, v0, 1.0
	v_sub_f32_e32 v1, 1.0, v0
.LBB0_506:
	s_add_i32 s6, s1, 1
	v_mov_b32_e32 v3, s0
	v_mov_b32_e32 v4, s6
	v_cndmask_b32_e64 v3, v3, v4, s[4:5]
	v_mad_u64_u32 v[4:5], s[6:7], v3, s14, v[162:163]
	ds_read_u16 v4, v4
	v_lshl_add_u32 v3, v3, 1, v199
	s_waitcnt lgkmcnt(0)
	v_lshlrev_b32_e32 v4, 16, v4
	v_mul_f32_e32 v4, 0xbfb8aa3b, v4
	v_exp_f32_e32 v4, v4
	s_nop 0
	v_add_f32_e32 v4, 1.0, v4
	v_div_scale_f32 v5, s[6:7], v4, v4, 1.0
	v_rcp_f32_e32 v6, v5
	s_add_i32 s6, s0, 1
	v_fma_f32 v7, -v5, v6, 1.0
	v_fmac_f32_e32 v6, v7, v6
	v_div_scale_f32 v7, vcc, 1.0, v4, 1.0
	v_mul_f32_e32 v8, v7, v6
	v_fma_f32 v9, -v5, v8, v7
	v_fmac_f32_e32 v8, v9, v6
	v_fma_f32 v5, -v5, v8, v7
	v_div_fmas_f32 v5, v5, v6, v8
	v_div_fixup_f32 v4, v5, v4, 1.0
	v_fma_f32 v4, v1, v4, v0
	v_sub_f32_e32 v5, 1.0, v4
	v_mul_f32_e32 v5, v2, v5
	v_cvt_pk_bf16_f32 v5, v5, s0
	ds_write_b16 v3, v5
	v_mul_f32_e32 v4, v2, v4
	v_mov_b32_e32 v2, s6
	v_mov_b32_e32 v3, s1
	v_cndmask_b32_e64 v5, v2, v3, s[4:5]
	v_mad_u64_u32 v[2:3], s[6:7], v5, s14, v[162:163]
	ds_read_u16 v2, v2
	s_add_i32 s1, s1, -2
	v_lshl_add_u32 v5, v5, 1, v199
	s_waitcnt lgkmcnt(0)
	v_lshlrev_b32_e32 v2, 16, v2
	v_mul_f32_e32 v2, 0xbfb8aa3b, v2
	v_exp_f32_e32 v2, v2
	s_nop 0
	v_add_f32_e32 v2, 1.0, v2
	v_div_scale_f32 v3, s[6:7], v2, v2, 1.0
	v_rcp_f32_e32 v6, v3
	s_nop 0
	v_fma_f32 v7, -v3, v6, 1.0
	v_fmac_f32_e32 v6, v7, v6
	v_div_scale_f32 v7, vcc, 1.0, v2, 1.0
	v_mul_f32_e32 v8, v7, v6
	v_fma_f32 v9, -v3, v8, v7
	v_fmac_f32_e32 v8, v9, v6
	v_fma_f32 v3, -v3, v8, v7
	v_div_fmas_f32 v3, v3, v6, v8
	v_div_fixup_f32 v2, v3, v2, 1.0
	v_fma_f32 v2, v1, v2, v0
	v_sub_f32_e32 v3, 1.0, v2
	v_mul_f32_e32 v3, v4, v3
	v_cvt_pk_bf16_f32 v3, v3, s0
	s_add_i32 s0, s0, 2
	v_mul_f32_e32 v2, v4, v2
	s_cmp_eq_u32 s0, 64
	ds_write_b16 v5, v3
	s_cbranch_scc0 .LBB0_506
	s_add_u32 s6, s66, s19
	v_lshl_add_u32 v0, s25, 8, v128
	s_addc_u32 s7, s67, 0
	s_lshl_b64 s[0:1], s[10:11], 1
	v_ashrrev_i32_e32 v1, 31, v0
	s_add_u32 s0, s6, s0
	v_lshl_add_u64 v[0:1], v[0:1], 2, s[2:3]
	s_addc_u32 s1, s7, s1
	global_store_dword v[0:1], v2, off
	v_lshl_add_u64 v[0:1], s[0:1], 0, v[150:151]
	s_mov_b64 s[0:1], 0x1800000
	v_lshl_add_u64 v[4:5], v[0:1], 0, s[0:1]
	v_mov_b32_e32 v139, v151
	v_lshl_add_u64 v[64:65], v[4:5], 0, v[138:139]
	s_waitcnt lgkmcnt(0)
	s_barrier
	global_load_dwordx4 v[64:67], v[64:65], off
	v_mov_b32_e32 v141, v151
	v_mov_b32_e32 v143, v151
	v_mov_b32_e32 v145, v151
	s_mov_b64 s[0:1], 0
	s_mov_b64 s[6:7], s[88:89]
	v_lshl_add_u64 v[68:69], v[4:5], 0, v[140:141]
	global_load_dwordx4 v[68:71], v[68:69], off
	v_lshl_add_u64 v[72:73], v[4:5], 0, v[142:143]
	global_load_dwordx4 v[72:75], v[72:73], off
	v_lshl_add_u64 v[76:77], v[4:5], 0, v[144:145]
	global_load_dwordx4 v[76:79], v[76:77], off
	s_waitcnt vmcnt(0)
	ds_write_b128 v175, v[64:67]
	ds_write_b128 v176, v[68:71]
	ds_write_b128 v177, v[72:75]
	ds_write_b128 v178, v[76:79]
.LBB0_508:
	s_and_b64 vcc, exec, s[0:1]
	s_cbranch_vccz .LBB0_513
	s_add_u32 s6, s66, s19
	s_addc_u32 s7, s67, 0
	s_ashr_i32 s11, s10, 31
	s_lshl_b64 s[0:1], s[10:11], 1
	s_add_u32 s0, s6, s0
	s_addc_u32 s1, s7, s1
	v_lshl_add_u64 v[16:17], s[0:1], 0, v[150:151]
	s_mov_b64 s[0:1], 0xc00000
	v_lshl_add_u64 v[4:5], v[16:17], 0, s[0:1]
	v_mov_b32_e32 v139, v151
	v_lshl_add_u64 v[64:65], v[4:5], 0, v[138:139]
	global_load_dwordx4 v[64:67], v[64:65], off
	v_mov_b32_e32 v141, v151
	v_mov_b32_e32 v143, v151
	v_mov_b32_e32 v145, v151
	v_lshl_add_u64 v[68:69], v[4:5], 0, v[140:141]
	global_load_dwordx4 v[68:71], v[68:69], off
	v_lshl_add_u64 v[72:73], v[4:5], 0, v[142:143]
	global_load_dwordx4 v[72:75], v[72:73], off
	v_lshl_add_u64 v[76:77], v[4:5], 0, v[144:145]
	global_load_dwordx4 v[76:79], v[76:77], off
	s_waitcnt vmcnt(0)
	ds_write_b128 v175, v[64:67]
	ds_write_b128 v176, v[68:71]
	ds_write_b128 v177, v[72:75]
	ds_write_b128 v178, v[76:79]
	v_lshl_add_u64 v[0:1], v[16:17], 0, v[138:139]
	global_load_dwordx4 v[12:15], v[0:1], off
	v_lshl_add_u64 v[0:1], v[16:17], 0, v[140:141]
	global_load_dwordx4 v[8:11], v[0:1], off
	v_lshl_add_u64 v[0:1], v[16:17], 0, v[142:143]
	global_load_dwordx4 v[4:7], v[0:1], off
	v_lshl_add_u64 v[0:1], v[16:17], 0, v[144:145]
	global_load_dwordx4 v[0:3], v[0:1], off
	s_mov_b64 s[0:1], exec
	v_readlane_b32 s6, v250, 58
	v_readlane_b32 s7, v250, 59
	s_and_b64 s[6:7], s[0:1], s[6:7]
	s_mov_b64 exec, s[6:7]
	s_cbranch_execz .LBB0_512
	v_or_b32_e32 v16, s10, v128
	v_ashrrev_i32_e32 v17, 31, v16
	v_lshlrev_b64 v[16:17], 6, v[16:17]
	v_lshl_add_u64 v[16:17], s[76:77], 0, v[16:17]
	s_lshl_b32 s30, s18, 2
	v_lshl_add_u64 v[16:17], v[16:17], 0, s[30:31]
	global_load_dword v18, v[16:17], off
	global_load_dword v19, v[16:17], off offset:16
	global_load_dword v20, v[16:17], off offset:32
	v_readlane_b32 s6, v250, 60
	global_load_dword v16, v[16:17], off offset:48
	v_readlane_b32 s7, v250, 61
	v_readlane_b32 s10, v250, 62
	v_readlane_b32 s11, v250, 63
	v_readlane_b32 s18, v249, 8
	v_readlane_b32 s19, v249, 9
	s_waitcnt vmcnt(1)
	v_max_f32_e32 v21, v20, v20
	v_min_f32_e32 v22, 0, v21
	v_mul_f32_e64 v21, |v20|, s15
	v_fma_f32 v23, |v20|, s15, -v21
	v_rndne_f32_e32 v24, v21
	v_fma_f32 v23, |v20|, s16, v23
	v_sub_f32_e32 v21, v21, v24
	v_add_f32_e32 v21, v21, v23
	v_exp_f32_e32 v21, v21
	v_cvt_i32_f32_e32 v23, v24
	v_cmp_ngt_f32_e64 vcc, |v20|, s17
	s_waitcnt vmcnt(0)
	v_mul_f32_e64 v17, |v16|, s15
	v_ldexp_f32 v21, v21, v23
	v_cndmask_b32_e32 v21, 0, v21, vcc
	v_cmp_nlt_f32_e64 vcc, |v20|, s20
	s_nop 1
	v_cndmask_b32_e32 v23, v225, v21, vcc
	v_add_f32_e32 v24, 1.0, v23
	v_add_f32_e32 v20, -1.0, v24
	v_sub_f32_e32 v21, v20, v24
	v_add_f32_e32 v21, 1.0, v21
	v_sub_f32_e32 v20, v23, v20
	v_add_f32_e32 v25, v20, v21
	v_frexp_mant_f32_e32 v20, v24
	v_cmp_gt_f32_e32 vcc, s21, v20
	v_cvt_f64_f32_e32 v[20:21], v24
	v_frexp_exp_i32_f64_e32 v20, v[20:21]
	v_subbrev_co_u32_e32 v20, vcc, 0, v20, vcc
	v_sub_u32_e32 v21, 0, v20
	v_ldexp_f32 v24, v24, v21
	v_ldexp_f32 v21, v25, v21
	v_add_f32_e32 v25, -1.0, v24
	v_add_f32_e32 v26, 1.0, v25
	v_sub_f32_e32 v26, v24, v26
	v_add_f32_e32 v26, v21, v26
	v_add_f32_e32 v27, v25, v26
	v_sub_f32_e32 v25, v25, v27
	v_add_f32_e32 v25, v26, v25
	v_add_f32_e32 v26, 1.0, v24
	v_add_f32_e32 v28, -1.0, v26
	v_sub_f32_e32 v24, v24, v28
	v_add_f32_e32 v21, v21, v24
	v_add_f32_e32 v24, v26, v21
	v_sub_f32_e32 v26, v26, v24
	v_add_f32_e32 v21, v21, v26
	v_rcp_f32_e32 v26, v24
	v_cvt_f32_i32_e32 v20, v20
	v_cmp_neq_f32_e32 vcc, s13, v23
	v_mul_f32_e32 v28, v27, v26
	v_mul_f32_e32 v29, v24, v28
	v_fma_f32 v30, v28, v24, -v29
	v_fmac_f32_e32 v30, v28, v21
	v_add_f32_e32 v31, v29, v30
	v_sub_f32_e32 v32, v27, v31
	v_sub_f32_e32 v27, v27, v32
	v_sub_f32_e32 v29, v31, v29
	v_sub_f32_e32 v27, v27, v31
	v_add_f32_e32 v25, v25, v27
	v_sub_f32_e32 v27, v29, v30
	v_add_f32_e32 v25, v27, v25
	v_add_f32_e32 v27, v32, v25
	v_mul_f32_e32 v29, v26, v27
	v_mul_f32_e32 v30, v24, v29
	v_fma_f32 v24, v29, v24, -v30
	v_fmac_f32_e32 v24, v29, v21
	v_sub_f32_e32 v21, v32, v27
	v_add_f32_e32 v21, v25, v21
	v_add_f32_e32 v25, v30, v24
	v_sub_f32_e32 v31, v27, v25
	v_sub_f32_e32 v27, v27, v31
	v_sub_f32_e32 v30, v25, v30
	v_sub_f32_e32 v25, v27, v25
	v_add_f32_e32 v21, v21, v25
	v_sub_f32_e32 v24, v30, v24
	v_add_f32_e32 v21, v24, v21
	v_add_f32_e32 v24, v28, v29
	v_add_f32_e32 v21, v31, v21
	v_sub_f32_e32 v25, v24, v28
	v_mul_f32_e32 v21, v26, v21
	v_sub_f32_e32 v25, v29, v25
	v_add_f32_e32 v21, v25, v21
	v_mul_f32_e32 v28, 0x3f317218, v20
	v_add_f32_e32 v25, v24, v21
	v_fma_f32 v29, v20, s22, -v28
	v_mul_f32_e32 v26, v25, v25
	v_fmac_f32_e32 v29, 0xb102e308, v20
	v_sub_f32_e32 v20, v25, v24
	v_fmamk_f32 v27, v26, 0x3e9b6dac, v204
	v_sub_f32_e32 v20, v21, v20
	v_add_f32_e32 v21, v28, v29
	v_fmaak_f32 v27, v26, v27, 0x3f2aaada
	v_sub_f32_e32 v24, v21, v28
	v_ldexp_f32 v28, v25, 1
	v_mul_f32_e32 v25, v25, v26
	v_mul_f32_e32 v25, v25, v27
	v_add_f32_e32 v26, v28, v25
	v_sub_f32_e32 v27, v26, v28
	v_ldexp_f32 v20, v20, 1
	v_sub_f32_e32 v25, v25, v27
	v_add_f32_e32 v20, v20, v25
	v_add_f32_e32 v25, v26, v20
	v_sub_f32_e32 v26, v25, v26
	v_sub_f32_e32 v20, v20, v26
	v_add_f32_e32 v26, v21, v25
	v_sub_f32_e32 v27, v26, v21
	v_sub_f32_e32 v28, v26, v27
	v_sub_f32_e32 v24, v29, v24
	v_sub_f32_e32 v21, v21, v28
	v_sub_f32_e32 v25, v25, v27
	v_add_f32_e32 v21, v25, v21
	v_add_f32_e32 v25, v24, v20
	v_sub_f32_e32 v27, v25, v24
	v_sub_f32_e32 v28, v25, v27
	v_sub_f32_e32 v24, v24, v28
	v_sub_f32_e32 v20, v20, v27
	v_add_f32_e32 v21, v25, v21
	v_add_f32_e32 v20, v20, v24
	v_add_f32_e32 v24, v26, v21
	v_sub_f32_e32 v25, v24, v26
	v_sub_f32_e32 v21, v21, v25
	v_add_f32_e32 v20, v20, v21
	v_add_f32_e32 v20, v24, v20
	v_cndmask_b32_e32 v20, v225, v20, vcc
	v_cmp_lt_f32_e64 vcc, |v23|, s23
	v_fma_f32 v21, |v16|, s15, -v17
	v_fma_f32 v21, |v16|, s16, v21
	v_cndmask_b32_e32 v20, v20, v23, vcc
	v_sub_f32_e32 v20, v22, v20
	v_rndne_f32_e32 v22, v17
	v_sub_f32_e32 v17, v17, v22
	v_add_f32_e32 v17, v17, v21
	v_exp_f32_e32 v17, v17
	v_cvt_i32_f32_e32 v21, v22
	v_cmp_ngt_f32_e64 vcc, |v16|, s17
	v_ldexp_f32 v17, v17, v21
	s_nop 0
	v_cndmask_b32_e32 v17, 0, v17, vcc
	v_cmp_nlt_f32_e64 vcc, |v16|, s20
	v_max_f32_e32 v16, v16, v16
	v_min_f32_e32 v16, 0, v16
	v_cndmask_b32_e32 v17, v225, v17, vcc
	v_add_f32_e32 v21, 1.0, v17
	v_add_f32_e32 v22, -1.0, v21
	v_sub_f32_e32 v23, v22, v21
	v_add_f32_e32 v23, 1.0, v23
	v_sub_f32_e32 v22, v17, v22
	v_add_f32_e32 v24, v22, v23
	v_frexp_mant_f32_e32 v22, v21
	v_cmp_gt_f32_e32 vcc, s21, v22
	v_cvt_f64_f32_e32 v[22:23], v21
	v_frexp_exp_i32_f64_e32 v22, v[22:23]
	v_subbrev_co_u32_e32 v22, vcc, 0, v22, vcc
	v_sub_u32_e32 v23, 0, v22
	v_ldexp_f32 v21, v21, v23
	v_ldexp_f32 v23, v24, v23
	v_add_f32_e32 v24, -1.0, v21
	v_add_f32_e32 v25, 1.0, v24
	v_sub_f32_e32 v25, v21, v25
	v_add_f32_e32 v25, v23, v25
	v_add_f32_e32 v26, v24, v25
	v_sub_f32_e32 v24, v24, v26
	v_add_f32_e32 v24, v25, v24
	v_add_f32_e32 v25, 1.0, v21
	v_add_f32_e32 v27, -1.0, v25
	v_sub_f32_e32 v21, v21, v27
	v_add_f32_e32 v21, v23, v21
	v_add_f32_e32 v23, v25, v21
	v_sub_f32_e32 v25, v25, v23
	v_add_f32_e32 v21, v21, v25
	v_rcp_f32_e32 v25, v23
	v_cvt_f32_i32_e32 v22, v22
	v_cmp_neq_f32_e32 vcc, s13, v17
	v_mul_f32_e32 v27, v26, v25
	v_mul_f32_e32 v28, v23, v27
	v_fma_f32 v29, v27, v23, -v28
	v_fmac_f32_e32 v29, v27, v21
	v_add_f32_e32 v30, v28, v29
	v_sub_f32_e32 v31, v26, v30
	v_sub_f32_e32 v26, v26, v31
	v_sub_f32_e32 v28, v30, v28
	v_sub_f32_e32 v26, v26, v30
	v_add_f32_e32 v24, v24, v26
	v_sub_f32_e32 v26, v28, v29
	v_add_f32_e32 v24, v26, v24
	v_add_f32_e32 v26, v31, v24
	v_mul_f32_e32 v28, v25, v26
	v_mul_f32_e32 v29, v23, v28
	v_fma_f32 v23, v28, v23, -v29
	v_fmac_f32_e32 v23, v28, v21
	v_sub_f32_e32 v21, v31, v26
	v_add_f32_e32 v21, v24, v21
	v_add_f32_e32 v24, v29, v23
	v_sub_f32_e32 v30, v26, v24
	v_sub_f32_e32 v26, v26, v30
	v_sub_f32_e32 v29, v24, v29
	v_sub_f32_e32 v24, v26, v24
	v_add_f32_e32 v21, v21, v24
	v_sub_f32_e32 v23, v29, v23
	v_add_f32_e32 v21, v23, v21
	v_add_f32_e32 v23, v27, v28
	v_add_f32_e32 v21, v30, v21
	v_sub_f32_e32 v24, v23, v27
	v_mul_f32_e32 v21, v25, v21
	v_sub_f32_e32 v24, v28, v24
	v_add_f32_e32 v21, v24, v21
	v_mul_f32_e32 v27, 0x3f317218, v22
	v_add_f32_e32 v24, v23, v21
	v_fma_f32 v28, v22, s22, -v27
	v_mul_f32_e32 v25, v24, v24
	v_fmac_f32_e32 v28, 0xb102e308, v22
	v_sub_f32_e32 v22, v24, v23
	v_fmamk_f32 v26, v25, 0x3e9b6dac, v204
	v_sub_f32_e32 v21, v21, v22
	v_add_f32_e32 v22, v27, v28
	v_fmaak_f32 v26, v25, v26, 0x3f2aaada
	v_sub_f32_e32 v23, v22, v27
	v_ldexp_f32 v27, v24, 1
	v_mul_f32_e32 v24, v24, v25
	v_mul_f32_e32 v24, v24, v26
	v_add_f32_e32 v25, v27, v24
	v_sub_f32_e32 v26, v25, v27
	v_ldexp_f32 v21, v21, 1
	v_sub_f32_e32 v24, v24, v26
	v_add_f32_e32 v21, v21, v24
	v_add_f32_e32 v24, v25, v21
	v_sub_f32_e32 v25, v24, v25
	v_sub_f32_e32 v21, v21, v25
	v_add_f32_e32 v25, v22, v24
	v_sub_f32_e32 v26, v25, v22
	v_sub_f32_e32 v27, v25, v26
	v_sub_f32_e32 v23, v28, v23
	v_sub_f32_e32 v22, v22, v27
	v_sub_f32_e32 v24, v24, v26
	v_add_f32_e32 v22, v24, v22
	v_add_f32_e32 v24, v23, v21
	v_sub_f32_e32 v26, v24, v23
	v_sub_f32_e32 v27, v24, v26
	v_sub_f32_e32 v23, v23, v27
	v_sub_f32_e32 v21, v21, v26
	v_add_f32_e32 v22, v24, v22
	v_add_f32_e32 v21, v21, v23
	v_add_f32_e32 v23, v25, v22
	v_sub_f32_e32 v24, v23, v25
	v_sub_f32_e32 v22, v22, v24
	v_add_f32_e32 v21, v21, v22
	v_add_f32_e32 v21, v23, v21
	v_cndmask_b32_e32 v21, v225, v21, vcc
	v_cmp_lt_f32_e64 vcc, |v17|, s23
	s_nop 1
	v_cndmask_b32_e32 v17, v21, v17, vcc
	v_cmp_lt_i32_e32 vcc, v207, v206
	s_nop 1
	v_cndmask_b32_e32 v21, v207, v205, vcc
	v_lshlrev_b32_e32 v21, 2, v21
	ds_bpermute_b32 v21, v21, v20
	v_cmp_lt_i32_e32 vcc, v208, v206
	s_waitcnt lgkmcnt(0)
	v_add_f32_e32 v21, v20, v21
	v_cndmask_b32_e64 v20, v21, v20, s[6:7]
	v_cndmask_b32_e32 v21, v208, v205, vcc
	v_lshlrev_b32_e32 v21, 2, v21
	ds_bpermute_b32 v21, v21, v20
	v_cmp_lt_i32_e32 vcc, v209, v206
	s_waitcnt lgkmcnt(0)
	v_add_f32_e32 v21, v20, v21
	v_cndmask_b32_e64 v20, v21, v20, s[10:11]
	v_cndmask_b32_e32 v21, v209, v205, vcc
	v_lshlrev_b32_e32 v21, 2, v21
	ds_bpermute_b32 v21, v21, v20
	v_readlane_b32 s10, v249, 0
	v_readlane_b32 s11, v249, 1
	v_cmp_lt_i32_e32 vcc, v210, v206
	s_waitcnt lgkmcnt(0)
	v_add_f32_e32 v21, v20, v21
	v_cndmask_b32_e64 v20, v21, v20, s[10:11]
	v_cndmask_b32_e32 v21, v210, v205, vcc
	v_lshlrev_b32_e32 v21, 2, v21
	ds_bpermute_b32 v21, v21, v20
	v_readlane_b32 s10, v249, 2
	v_readlane_b32 s11, v249, 3
	v_cmp_lt_i32_e32 vcc, v211, v206
	s_waitcnt lgkmcnt(0)
	v_add_f32_e32 v21, v20, v21
	v_cndmask_b32_e64 v20, v21, v20, s[10:11]
	v_cndmask_b32_e32 v21, v211, v205, vcc
	v_lshlrev_b32_e32 v21, 2, v21
	ds_bpermute_b32 v21, v21, v20
	v_readlane_b32 s10, v249, 4
	v_readlane_b32 s11, v249, 5
	v_cmp_lt_i32_e32 vcc, v212, v206
	s_waitcnt lgkmcnt(0)
	v_add_f32_e32 v21, v20, v21
	v_cndmask_b32_e64 v20, v21, v20, s[10:11]
	v_cndmask_b32_e32 v21, v212, v205, vcc
	v_lshlrev_b32_e32 v21, 2, v21
	ds_bpermute_b32 v21, v21, v20
	v_readlane_b32 s10, v249, 6
	v_readlane_b32 s11, v249, 7
	v_cmp_lt_i32_e32 vcc, v215, v214
	s_waitcnt lgkmcnt(0)
	v_add_f32_e32 v21, v20, v21
	v_cndmask_b32_e64 v20, v21, v20, s[10:11]
	v_sub_f32_e32 v21, v16, v17
	ds_bpermute_b32 v16, v213, v20
	s_waitcnt lgkmcnt(0)
	v_sub_f32_e32 v17, v16, v20
	v_add_f32_e32 v18, v18, v17
	v_cndmask_b32_e32 v17, v205, v215, vcc
	v_lshlrev_b32_e32 v20, 2, v17
	ds_bpermute_b32 v17, v20, v18
	v_cmp_lt_i32_e32 vcc, v216, v214
	s_waitcnt lgkmcnt(0)
	v_max_f32_e32 v17, v17, v17
	v_cndmask_b32_e32 v22, v205, v216, vcc
	v_max_f32_e32 v17, v18, v17
	v_lshlrev_b32_e32 v22, 2, v22
	ds_bpermute_b32 v23, v22, v17
	v_cmp_lt_i32_e32 vcc, v217, v214
	s_waitcnt lgkmcnt(0)
	v_max_f32_e32 v23, v23, v23
	v_max_f32_e32 v17, v17, v23
	v_cndmask_b32_e32 v23, v205, v217, vcc
	v_lshlrev_b32_e32 v23, 2, v23
	ds_bpermute_b32 v24, v23, v17
	v_cmp_lt_i32_e32 vcc, v218, v214
	s_waitcnt lgkmcnt(0)
	v_max_f32_e32 v24, v24, v24
	v_max_f32_e32 v17, v17, v24
	v_cndmask_b32_e32 v24, v205, v218, vcc
	v_lshlrev_b32_e32 v24, 2, v24
	ds_bpermute_b32 v25, v24, v17
	v_cmp_lt_i32_e32 vcc, v219, v214
	s_waitcnt lgkmcnt(0)
	v_max_f32_e32 v25, v25, v25
	v_max_f32_e32 v17, v17, v25
	v_cndmask_b32_e32 v25, v205, v219, vcc
	v_lshlrev_b32_e32 v25, 2, v25
	ds_bpermute_b32 v26, v25, v17
	v_cmp_lt_i32_e32 vcc, v220, v214
	s_waitcnt lgkmcnt(0)
	v_max_f32_e32 v26, v26, v26
	v_max_f32_e32 v17, v17, v26
	v_cndmask_b32_e32 v26, v205, v220, vcc
	v_lshlrev_b32_e32 v26, 2, v26
	ds_bpermute_b32 v27, v26, v17
	s_waitcnt lgkmcnt(0)
	v_max_f32_e32 v27, v27, v27
	v_max_f32_e32 v17, v17, v27
	v_sub_f32_e32 v18, v18, v17
	v_mul_f32_e32 v27, 0x3fb8aa3b, v18
	v_fma_f32 v28, v18, s8, -v27
	v_rndne_f32_e32 v29, v27
	v_fmac_f32_e32 v28, 0x32a5705f, v18
	v_sub_f32_e32 v27, v27, v29
	v_add_f32_e32 v27, v27, v28
	v_exp_f32_e32 v27, v27
	v_cvt_i32_f32_e32 v28, v29
	v_cmp_ngt_f32_e32 vcc, s9, v18
	v_ldexp_f32 v27, v27, v28
	s_nop 0
	v_cndmask_b32_e32 v27, 0, v27, vcc
	v_cmp_nlt_f32_e32 vcc, s12, v18
	s_nop 1
	v_cndmask_b32_e32 v27, v225, v27, vcc
	v_cmp_ne_u32_e32 vcc, 63, v221
	s_nop 1
	v_addc_co_u32_e32 v18, vcc, 0, v205, vcc
	v_lshlrev_b32_e32 v18, 2, v18
	ds_bpermute_b32 v18, v18, v21
	v_cmp_gt_u32_e32 vcc, 62, v221
	s_waitcnt lgkmcnt(0)
	v_add_f32_e32 v18, v21, v18
	v_cndmask_b32_e64 v18, v18, v21, s[18:19]
	v_cndmask_b32_e64 v21, 0, 2, vcc
	v_add_lshl_u32 v21, v21, v205, 2
	ds_bpermute_b32 v21, v21, v18
	v_readlane_b32 s18, v249, 10
	v_readlane_b32 s19, v249, 11
	v_cmp_gt_u32_e32 vcc, 60, v221
	s_waitcnt lgkmcnt(0)
	v_add_f32_e32 v21, v18, v21
	v_cndmask_b32_e64 v18, v18, v21, s[18:19]
	v_cndmask_b32_e64 v21, 0, 4, vcc
	v_add_lshl_u32 v21, v21, v205, 2
	ds_bpermute_b32 v21, v21, v18
	v_readlane_b32 s18, v249, 12
	v_readlane_b32 s19, v249, 13
	v_cmp_gt_u32_e32 vcc, 56, v221
	s_waitcnt lgkmcnt(0)
	v_add_f32_e32 v21, v18, v21
	v_cndmask_b32_e64 v18, v18, v21, s[18:19]
	v_cndmask_b32_e64 v21, 0, 8, vcc
	v_add_lshl_u32 v21, v21, v205, 2
	ds_bpermute_b32 v21, v21, v18
	v_readlane_b32 s18, v249, 14
	v_readlane_b32 s19, v249, 15
	v_cmp_gt_u32_e32 vcc, 48, v221
	s_waitcnt lgkmcnt(0)
	v_add_f32_e32 v21, v18, v21
	v_cndmask_b32_e64 v18, v18, v21, s[18:19]
	v_cndmask_b32_e64 v21, 0, 16, vcc
	v_add_lshl_u32 v21, v21, v205, 2
	ds_bpermute_b32 v21, v21, v18
	v_readlane_b32 s18, v249, 16
	v_readlane_b32 s19, v249, 17
	s_waitcnt lgkmcnt(0)
	v_add_f32_e32 v21, v18, v21
	v_cndmask_b32_e64 v18, v18, v21, s[18:19]
	ds_bpermute_b32 v21, v222, v18
	s_waitcnt lgkmcnt(0)
	v_add_f32_e32 v21, v18, v21
	v_cndmask_b32_e64 v21, v18, v21, s[10:11]
	ds_bpermute_b32 v18, v224, v21
	s_waitcnt lgkmcnt(0)
	v_sub_f32_e32 v21, v18, v21
	v_add_f32_e32 v21, v19, v21
	ds_bpermute_b32 v19, v20, v21
	s_waitcnt lgkmcnt(0)
	v_max_f32_e32 v19, v19, v19
	v_max_f32_e32 v19, v21, v19
	ds_bpermute_b32 v20, v22, v19
	s_waitcnt lgkmcnt(0)
	v_max_f32_e32 v20, v20, v20
	v_max_f32_e32 v19, v19, v20
	ds_bpermute_b32 v20, v23, v19
	s_waitcnt lgkmcnt(0)
	v_max_f32_e32 v20, v20, v20
	v_max_f32_e32 v19, v19, v20
	ds_bpermute_b32 v20, v24, v19
	s_waitcnt lgkmcnt(0)
	v_max_f32_e32 v20, v20, v20
	v_max_f32_e32 v19, v19, v20
	ds_bpermute_b32 v20, v25, v19
	s_waitcnt lgkmcnt(0)
	v_max_f32_e32 v20, v20, v20
	v_max_f32_e32 v19, v19, v20
	ds_bpermute_b32 v20, v26, v19
	s_waitcnt lgkmcnt(0)
	v_max_f32_e32 v20, v20, v20
	v_max_f32_e32 v19, v19, v20
	v_sub_f32_e32 v20, v21, v19
	v_mul_f32_e32 v21, 0x3fb8aa3b, v20
	v_fma_f32 v22, v20, s8, -v21
	v_rndne_f32_e32 v23, v21
	v_fmac_f32_e32 v22, 0x32a5705f, v20
	v_sub_f32_e32 v21, v21, v23
	v_add_f32_e32 v21, v21, v22
	v_exp_f32_e32 v21, v21
	v_cvt_i32_f32_e32 v22, v23
	v_cmp_ngt_f32_e32 vcc, s9, v20
	v_ldexp_f32 v21, v21, v22
	s_nop 0
	v_cndmask_b32_e32 v21, 0, v21, vcc
	v_cmp_nlt_f32_e32 vcc, s12, v20
	s_nop 1
	v_cndmask_b32_e32 v20, v225, v21, vcc
	ds_write2st64_b32 v197, v27, v20 offset0:216 offset1:217
	s_and_b64 exec, exec, s[6:7]
	s_cbranch_execz .LBB0_512
	s_lshl_b32 s6, s25, 3
	s_ashr_i32 s7, s6, 31
	s_lshl_b64 s[6:7], s[6:7], 2
	s_add_u32 s6, s64, s6
	s_addc_u32 s7, s65, s7
	global_store_dwordx2 v151, v[16:17], s[6:7]
	global_store_dwordx2 v151, v[18:19], s[6:7] offset:16

.LBB0_753:
	s_cmpk_lt_i32 s29, 0x300
	s_cselect_b32 s23, 0, 0xfffffd00
	s_add_i32 s23, s23, s29
	s_lshl_b32 s6, s23, 4
	s_and_b32 s58, s6, 0xffffffc0
	s_lshl_b32 s80, s23, 1
	s_and_b32 s20, s29, 3
	s_or_b32 s60, s80, 1
	s_ashr_i32 s59, s58, 31
	s_mul_i32 s7, s58, 0x1c00
	s_mul_hi_i32 s6, s58, 0x1c00
	s_add_u32 s65, s62, s7
	s_addc_u32 s83, s63, s6
	s_cmpk_gt_i32 s29, 0x2ff
	s_mov_b64 s[6:7], -1
	s_mul_i32 s64, s20, 0x300000
	s_cbranch_scc0 .LBB0_757
	s_lshl_b32 s6, s20, 7
	s_lshl_b32 s7, s20, 8
	s_add_u32 s10, s65, s7
	s_addc_u32 s11, s83, 0
	v_lshl_add_u64 v[4:5], s[10:11], 0, v[154:155]
	s_mov_b64 s[10:11], 0x1000
	v_lshl_add_u64 v[6:7], v[4:5], 0, s[10:11]
	v_mov_b32_e32 v131, v155
	v_lshl_add_u64 v[12:13], v[6:7], 0, v[130:131]
	global_load_dwordx4 v[12:15], v[12:13], off
	v_mov_b32_e32 v133, v155
	v_mov_b32_e32 v135, v155
	v_mov_b32_e32 v137, v155
	s_mov_b64 s[10:11], 0x1400
	v_lshl_add_u64 v[8:9], v[4:5], 0, v[132:133]
	v_lshl_add_u64 v[10:11], v[4:5], 0, v[134:135]
	v_readlane_b32 s36, v250, 28
	v_readlane_b32 s37, v250, 29
	s_mov_b32 s7, 0
	v_readlane_b32 s38, v250, 30
	v_readlane_b32 s39, v250, 31
	v_readlane_b32 s40, v250, 32
	v_readlane_b32 s41, v250, 33
	v_readlane_b32 s42, v250, 34
	v_readlane_b32 s43, v250, 35
	v_readlane_b32 s44, v250, 36
	v_readlane_b32 s45, v250, 37
	v_readlane_b32 s46, v250, 38
	v_readlane_b32 s47, v250, 39
	v_readlane_b32 s48, v250, 40
	v_readlane_b32 s49, v250, 41
	v_readlane_b32 s50, v250, 42
	v_readlane_b32 s51, v250, 43
	v_lshl_add_u64 v[16:17], v[6:7], 0, v[132:133]
	global_load_dwordx4 v[16:19], v[16:17], off
	v_lshl_add_u64 v[20:21], v[6:7], 0, v[134:135]
	global_load_dwordx4 v[20:23], v[20:21], off
	v_lshl_add_u64 v[24:25], v[6:7], 0, v[136:137]
	global_load_dwordx4 v[24:27], v[24:25], off
	v_lshl_add_u64 v[6:7], v[4:5], 0, s[10:11]
	v_lshl_add_u64 v[28:29], v[6:7], 0, v[130:131]
	global_load_dwordx4 v[28:31], v[28:29], off
	v_lshl_add_u64 v[32:33], v[6:7], 0, v[132:133]
	global_load_dwordx4 v[32:35], v[32:33], off
	v_lshl_add_u64 v[52:53], v[6:7], 0, v[134:135]
	global_load_dwordx4 v[52:55], v[52:53], off
	v_lshl_add_u64 v[56:57], v[6:7], 0, v[136:137]
	global_load_dwordx4 v[56:59], v[56:57], off
	s_waitcnt vmcnt(0)
	ds_write_b128 v39, v[12:15]
	ds_write_b128 v68, v[16:19]
	ds_write_b128 v69, v[20:23]
	ds_write_b128 v70, v[24:27]
	ds_write_b128 v71, v[28:31]
	ds_write_b128 v72, v[32:35]
	ds_write_b128 v73, v[52:55]
	ds_write_b128 v74, v[56:59]
	v_lshl_add_u64 v[6:7], v[4:5], 0, v[130:131]
	v_lshl_add_u64 v[4:5], v[4:5], 0, v[136:137]
	global_load_dwordx4 v[12:15], v[6:7], off offset:3072
	global_load_dwordx4 v[16:19], v[8:9], off offset:3072
	global_load_dwordx4 v[20:23], v[10:11], off offset:3072
	global_load_dwordx4 v[24:27], v[4:5], off offset:3072
	global_load_dwordx4 v[28:31], v[6:7], off offset:3072
	global_load_dwordx4 v[32:35], v[8:9], off offset:3072
	global_load_dwordx4 v[52:55], v[10:11], off offset:3072
	global_load_dwordx4 v[56:59], v[4:5], off offset:3072
	s_waitcnt vmcnt(0)
	ds_write_b128 v170, v[12:15]
	ds_write_b128 v171, v[16:19]
	ds_write_b128 v172, v[20:23]
	ds_write_b128 v173, v[24:27]
	ds_write_b128 v75, v[28:31]
	ds_write_b128 v76, v[32:35]
	ds_write_b128 v77, v[52:55]
	ds_write_b128 v78, v[56:59]
	v_or_b32_e32 v0, s6, v168
	v_lshlrev_b32_e32 v0, 2, v0
	s_waitcnt lgkmcnt(0)
	s_barrier
	global_load_dword v1, v0, s[36:37] offset:2048
	s_nop 0
	global_load_dword v0, v0, s[36:37]
	s_waitcnt vmcnt(0)
	v_sub_f32_e32 v0, v1, v0
	v_mul_f32_e32 v1, 0x3fb8aa3b, v0
	v_fma_f32 v2, v0, s28, -v1
	v_rndne_f32_e32 v3, v1
	v_fmac_f32_e32 v2, 0x32a5705f, v0
	v_sub_f32_e32 v1, v1, v3
	v_add_f32_e32 v1, v1, v2
	v_exp_f32_e32 v1, v1
	v_cvt_i32_f32_e32 v2, v3
	v_cmp_ngt_f32_e32 vcc, s15, v0
	v_ldexp_f32 v1, v1, v2
	s_nop 0
	v_cndmask_b32_e32 v1, 0, v1, vcc
	v_cmp_nlt_f32_e32 vcc, s22, v0
	v_mov_b32_e32 v2, 1.0
	s_nop 0
	v_cndmask_b32_e32 v0, v228, v1, vcc
	v_add_f32_e32 v0, 1.0, v0
	v_div_scale_f32 v1, s[10:11], v0, v0, 1.0
	v_rcp_f32_e32 v3, v1
	s_mov_b32 s10, 62
	v_fma_f32 v4, -v1, v3, 1.0
	v_fmac_f32_e32 v3, v4, v3
	v_div_scale_f32 v4, vcc, 1.0, v0, 1.0
	v_mul_f32_e32 v5, v4, v3
	v_fma_f32 v6, -v1, v5, v4
	v_fmac_f32_e32 v5, v6, v3
	v_fma_f32 v1, -v1, v5, v4
	v_div_fmas_f32 v1, v1, v3, v5
	v_div_fixup_f32 v0, v1, v0, 1.0
	v_sub_f32_e32 v1, 1.0, v0
.LBB0_755:
	s_add_i32 s11, s10, 1
	v_mov_b32_e32 v3, s11
	v_mov_b32_e32 v4, s7
	v_cndmask_b32_e64 v3, v3, v4, s[4:5]
	v_mul_lo_u32 v3, v3, s14
	v_add_lshl_u32 v3, v3, v168, 1
	v_add_u32_e32 v4, v80, v3
	ds_read_u16 v5, v4
	v_add_u32_e32 v3, v79, v3
	s_add_i32 s11, s7, 1
	s_add_i32 s7, s7, 2
	s_waitcnt lgkmcnt(0)
	v_lshlrev_b32_e32 v5, 16, v5
	v_mul_f32_e32 v5, 0xbfb8aa3b, v5
	v_exp_f32_e32 v5, v5
	s_nop 0
	v_add_f32_e32 v5, 1.0, v5
	v_div_scale_f32 v6, s[12:13], v5, v5, 1.0
	v_rcp_f32_e32 v7, v6
	s_nop 0
	v_fma_f32 v8, -v6, v7, 1.0
	v_fmac_f32_e32 v7, v8, v7
	v_div_scale_f32 v8, vcc, 1.0, v5, 1.0
	v_mul_f32_e32 v9, v8, v7
	v_fma_f32 v10, -v6, v9, v8
	v_fmac_f32_e32 v9, v10, v7
	v_fma_f32 v6, -v6, v9, v8
	v_div_fmas_f32 v6, v6, v7, v9
	v_div_fixup_f32 v5, v6, v5, 1.0
	ds_read_u16 v6, v3
	v_fma_f32 v5, v1, v5, v0
	v_mul_f32_e32 v2, v2, v5
	s_waitcnt lgkmcnt(0)
	v_lshlrev_b32_e32 v6, 16, v6
	v_mul_f32_e32 v6, v2, v6
	v_cvt_pk_bf16_f32 v6, v6, s0
	ds_write_b16 v3, v6
	v_sub_f32_e32 v3, 1.0, v5
	v_max_f32_e32 v5, 0x5bf68a9, v2
	v_div_scale_f32 v6, s[12:13], v5, v5, 1.0
	v_rcp_f32_e32 v7, v6
	s_nop 0
	v_fma_f32 v8, -v6, v7, 1.0
	v_fmac_f32_e32 v7, v8, v7
	v_div_scale_f32 v8, vcc, 1.0, v5, 1.0
	v_mul_f32_e32 v9, v8, v7
	v_fma_f32 v10, -v6, v9, v8
	v_fmac_f32_e32 v9, v10, v7
	v_fma_f32 v6, -v6, v9, v8
	v_div_fmas_f32 v6, v6, v7, v9
	v_div_fixup_f32 v5, v6, v5, 1.0
	v_mul_f32_e32 v3, v3, v5
	v_cvt_pk_bf16_f32 v3, v3, s0
	ds_write_b16 v4, v3
	v_mov_b32_e32 v3, s10
	v_mov_b32_e32 v4, s11
	v_cndmask_b32_e64 v3, v3, v4, s[4:5]
	v_mul_lo_u32 v3, v3, s14
	v_add_lshl_u32 v3, v3, v168, 1
	v_add_u32_e32 v4, v80, v3
	ds_read_u16 v5, v4
	v_add_u32_e32 v3, v79, v3
	s_add_i32 s10, s10, -2
	s_cmp_eq_u32 s7, 64
	s_waitcnt lgkmcnt(0)
	v_lshlrev_b32_e32 v5, 16, v5
	v_mul_f32_e32 v5, 0xbfb8aa3b, v5
	v_exp_f32_e32 v5, v5
	s_nop 0
	v_add_f32_e32 v5, 1.0, v5
	v_div_scale_f32 v6, s[12:13], v5, v5, 1.0
	v_rcp_f32_e32 v7, v6
	s_nop 0
	v_fma_f32 v8, -v6, v7, 1.0
	v_fmac_f32_e32 v7, v8, v7
	v_div_scale_f32 v8, vcc, 1.0, v5, 1.0
	v_mul_f32_e32 v9, v8, v7
	v_fma_f32 v10, -v6, v9, v8
	v_fmac_f32_e32 v9, v10, v7
	v_fma_f32 v6, -v6, v9, v8
	v_div_fmas_f32 v6, v6, v7, v9
	v_div_fixup_f32 v5, v6, v5, 1.0
	ds_read_u16 v6, v3
	v_fma_f32 v5, v1, v5, v0
	v_mul_f32_e32 v2, v2, v5
	s_waitcnt lgkmcnt(0)
	v_lshlrev_b32_e32 v6, 16, v6
	v_mul_f32_e32 v6, v2, v6
	v_cvt_pk_bf16_f32 v6, v6, s0
	ds_write_b16 v3, v6
	v_sub_f32_e32 v3, 1.0, v5
	v_max_f32_e32 v5, 0x5bf68a9, v2
	v_div_scale_f32 v6, s[12:13], v5, v5, 1.0
	v_rcp_f32_e32 v7, v6
	s_nop 0
	v_fma_f32 v8, -v6, v7, 1.0
	v_fmac_f32_e32 v7, v8, v7
	v_div_scale_f32 v8, vcc, 1.0, v5, 1.0
	v_mul_f32_e32 v9, v8, v7
	v_fma_f32 v10, -v6, v9, v8
	v_fmac_f32_e32 v9, v10, v7
	v_fma_f32 v6, -v6, v9, v8
	v_div_fmas_f32 v6, v6, v7, v9
	v_div_fixup_f32 v5, v6, v5, 1.0
	v_mul_f32_e32 v3, v3, v5
	v_cvt_pk_bf16_f32 v3, v3, s0
	ds_write_b16 v4, v3
	s_cbranch_scc0 .LBB0_755
	s_waitcnt lgkmcnt(0)
	s_barrier
	ds_read_b128 v[0:3], v81
	ds_read_b128 v[32:35], v81 offset:32
	ds_read_b128 v[4:7], v82 offset:34816
	ds_read_b128 v[50:53], v82 offset:34848
	s_waitcnt lgkmcnt(1)
	v_mfma_f32_32x32x16_bf16 v[0:15], v[0:3], v[4:7], 0
	ds_read_b128 v[16:19], v81 offset:17408
	ds_read_b128 v[20:23], v82 offset:53248
	v_readlane_b32 s10, v249, 24
	v_readlane_b32 s11, v249, 25
	s_ashr_i32 s81, s80, 31
	s_ashr_i32 s61, s60, 31
	v_mov_b32_e32 v151, v155
	v_mov_b32_e32 v139, v155
	s_waitcnt lgkmcnt(0)
	v_mfma_f32_32x32x16_bf16 v[16:31], v[16:19], v[20:23], 0
	v_mov_b32_e32 v141, v155
	v_mov_b32_e32 v143, v155
	v_mov_b32_e32 v145, v155
	v_add_u32_e32 v66, v169, v196
	v_add_u32_e32 v67, v169, v198
	s_mov_b32 s44, 0x800000
	v_mfma_f32_32x32x16_bf16 v[0:15], v[32:35], v[50:53], v[0:15]
	ds_read_b128 v[32:35], v81 offset:17440
	ds_read_b128 v[50:53], v82 offset:53280
	s_waitcnt lgkmcnt(0)
	v_mfma_f32_32x32x16_bf16 v[16:31], v[32:35], v[50:53], v[16:31]
	ds_read_b128 v[32:35], v81 offset:64
	ds_read_b128 v[50:53], v82 offset:34880
	s_waitcnt lgkmcnt(0)
	v_mfma_f32_32x32x16_bf16 v[0:15], v[32:35], v[50:53], v[0:15]
	ds_read_b128 v[32:35], v81 offset:17472
	ds_read_b128 v[50:53], v82 offset:53312
	s_waitcnt lgkmcnt(0)
	v_mfma_f32_32x32x16_bf16 v[16:31], v[32:35], v[50:53], v[16:31]
	ds_read_b128 v[32:35], v81 offset:96
	ds_read_b128 v[50:53], v82 offset:34912
	s_waitcnt lgkmcnt(0)
	v_mfma_f32_32x32x16_bf16 v[0:15], v[32:35], v[50:53], v[0:15]
	ds_read_b128 v[32:35], v81 offset:17504
	ds_read_b128 v[50:53], v82 offset:53344
	s_waitcnt lgkmcnt(0)
	v_mfma_f32_32x32x16_bf16 v[16:31], v[32:35], v[50:53], v[16:31]
	ds_read_b128 v[32:35], v81 offset:128
	ds_read_b128 v[50:53], v82 offset:34944
	s_waitcnt lgkmcnt(0)
	v_mfma_f32_32x32x16_bf16 v[0:15], v[32:35], v[50:53], v[0:15]
	ds_read_b128 v[32:35], v81 offset:17536
	ds_read_b128 v[50:53], v82 offset:53376
	s_waitcnt lgkmcnt(0)
	v_mfma_f32_32x32x16_bf16 v[16:31], v[32:35], v[50:53], v[16:31]
	ds_read_b128 v[32:35], v81 offset:160
	ds_read_b128 v[50:53], v82 offset:34976
	s_waitcnt lgkmcnt(0)
	v_mfma_f32_32x32x16_bf16 v[0:15], v[32:35], v[50:53], v[0:15]
	ds_read_b128 v[32:35], v81 offset:17568
	ds_read_b128 v[50:53], v82 offset:53408
	s_waitcnt lgkmcnt(0)
	v_mfma_f32_32x32x16_bf16 v[16:31], v[32:35], v[50:53], v[16:31]
	ds_read_b128 v[32:35], v81 offset:192
	ds_read_b128 v[50:53], v82 offset:35008
	s_waitcnt lgkmcnt(0)
	v_mfma_f32_32x32x16_bf16 v[0:15], v[32:35], v[50:53], v[0:15]
	ds_read_b128 v[32:35], v81 offset:17600
	ds_read_b128 v[50:53], v82 offset:53440
	s_waitcnt lgkmcnt(0)
	v_mfma_f32_32x32x16_bf16 v[16:31], v[32:35], v[50:53], v[16:31]
	ds_read_b128 v[32:35], v81 offset:224
	ds_read_b128 v[50:53], v82 offset:35040
	s_waitcnt lgkmcnt(0)
	v_mfma_f32_32x32x16_bf16 v[0:15], v[32:35], v[50:53], v[0:15]
	ds_read_b128 v[32:35], v81 offset:17632
	ds_read_b128 v[50:53], v82 offset:53472
	s_waitcnt lgkmcnt(0)
	v_mfma_f32_32x32x16_bf16 v[16:31], v[32:35], v[50:53], v[16:31]
	s_nop 7
	v_cndmask_b32_e64 v0, v0, 0, s[56:57]
	s_nop 2
	v_cndmask_b32_e64 v16, v16, 0, s[10:11]
	v_readlane_b32 s10, v249, 28
	v_readlane_b32 s11, v249, 29
	v_add_f32_e32 v50, v0, v16
	s_nop 0
	v_cndmask_b32_e64 v0, v1, 0, s[10:11]
	v_readlane_b32 s10, v249, 32
	v_cndmask_b32_e64 v1, 0, v17, s[56:57]
	v_readlane_b32 s11, v249, 33
	v_add_f32_e32 v51, v0, v1
	s_nop 0
	v_cndmask_b32_e64 v0, v2, 0, s[10:11]
	v_readlane_b32 s10, v249, 36
	v_readlane_b32 s11, v249, 37
	s_nop 1
	v_cndmask_b32_e64 v1, v18, 0, s[10:11]
	v_readlane_b32 s10, v249, 40
	v_readlane_b32 s11, v249, 41
	v_add_f32_e32 v52, v0, v1
	s_nop 0
	v_cndmask_b32_e64 v0, v3, 0, s[10:11]
	v_readlane_b32 s10, v249, 44
	v_readlane_b32 s11, v249, 45
	s_nop 1
	v_cndmask_b32_e64 v1, v19, 0, s[10:11]
	v_readlane_b32 s10, v249, 48
	v_readlane_b32 s11, v249, 49
	v_add_f32_e32 v53, v0, v1
	s_nop 0
	v_cndmask_b32_e64 v0, v4, 0, s[10:11]
	v_readlane_b32 s10, v249, 52
	v_readlane_b32 s11, v249, 53
	s_nop 1
	v_cndmask_b32_e64 v1, v20, 0, s[10:11]
	v_readlane_b32 s10, v249, 56
	v_readlane_b32 s11, v249, 57
	v_add_f32_e32 v54, v0, v1
	s_nop 0
	v_cndmask_b32_e64 v0, v5, 0, s[10:11]
	v_readlane_b32 s10, v249, 60
	v_readlane_b32 s11, v249, 61
	s_nop 1
	v_cndmask_b32_e64 v1, v21, 0, s[10:11]
	v_readlane_b32 s10, v248, 0
	v_readlane_b32 s11, v248, 1
	v_add_f32_e32 v55, v0, v1
	s_nop 0
	v_cndmask_b32_e64 v0, v6, 0, s[10:11]
	v_readlane_b32 s10, v248, 4
	v_readlane_b32 s11, v248, 5
	s_nop 1
	v_cndmask_b32_e64 v1, v22, 0, s[10:11]
	v_readlane_b32 s10, v248, 8
	v_readlane_b32 s11, v248, 9
	v_add_f32_e32 v56, v0, v1
	s_nop 0
	v_cndmask_b32_e64 v0, v7, 0, s[10:11]
	v_readlane_b32 s10, v248, 12
	v_readlane_b32 s11, v248, 13
	s_nop 1
	v_cndmask_b32_e64 v1, v23, 0, s[10:11]
	v_readlane_b32 s10, v248, 16
	v_readlane_b32 s11, v248, 17
	v_add_f32_e32 v57, v0, v1
	s_nop 0
	v_cndmask_b32_e64 v0, v8, 0, s[10:11]
	v_readlane_b32 s10, v248, 20
	v_readlane_b32 s11, v248, 21
	s_nop 1
	v_cndmask_b32_e64 v1, v24, 0, s[10:11]
	v_readlane_b32 s10, v248, 24
	v_readlane_b32 s11, v248, 25
	v_add_f32_e32 v58, v0, v1
	s_nop 0
	v_cndmask_b32_e64 v0, v9, 0, s[10:11]
	v_readlane_b32 s10, v248, 28
	v_readlane_b32 s11, v248, 29
	s_nop 1
	v_cndmask_b32_e64 v1, v25, 0, s[10:11]
	v_readlane_b32 s10, v248, 32
	v_readlane_b32 s11, v248, 33
	v_add_f32_e32 v59, v0, v1
	s_nop 0
	v_cndmask_b32_e64 v0, v10, 0, s[10:11]
	v_readlane_b32 s10, v248, 36
	v_readlane_b32 s11, v248, 37
	s_nop 1
	v_cndmask_b32_e64 v1, v26, 0, s[10:11]
	v_readlane_b32 s10, v248, 40
	v_readlane_b32 s11, v248, 41
	v_add_f32_e32 v60, v0, v1
	s_nop 0
	v_cndmask_b32_e64 v0, v11, 0, s[10:11]
	v_readlane_b32 s10, v248, 44
	v_readlane_b32 s11, v248, 45
	s_nop 1
	v_cndmask_b32_e64 v1, v27, 0, s[10:11]
	v_readlane_b32 s10, v248, 48
	v_readlane_b32 s11, v248, 49
	v_add_f32_e32 v61, v0, v1
	s_nop 0
	v_cndmask_b32_e64 v0, v12, 0, s[10:11]
	v_readlane_b32 s10, v248, 52
	v_readlane_b32 s11, v248, 53
	s_nop 1
	v_cndmask_b32_e64 v1, v28, 0, s[10:11]
	v_readlane_b32 s10, v248, 56
	v_readlane_b32 s11, v248, 57
	v_add_f32_e32 v62, v0, v1
	s_nop 0
	v_cndmask_b32_e64 v0, v13, 0, s[10:11]
	v_readlane_b32 s10, v248, 60
	v_readlane_b32 s11, v248, 61
	s_nop 1
	v_cndmask_b32_e64 v1, v29, 0, s[10:11]
	v_add_f32_e32 v63, v0, v1
	v_cndmask_b32_e64 v0, v14, 0, s[86:87]
	v_cndmask_b32_e64 v1, v30, 0, s[52:53]
	s_lshl_b64 s[10:11], s[80:81], 15
	v_add_f32_e32 v64, v0, v1
	v_cndmask_b32_e64 v0, v15, 0, s[2:3]
	v_cndmask_b32_e64 v1, v31, 0, s[0:1]
	v_lshl_add_u64 v[32:33], v[36:37], 0, s[10:11]
	s_lshl_b64 s[10:11], s[60:61], 15
	v_add_f32_e32 v65, v0, v1
	v_lshl_add_u64 v[34:35], v[36:37], 0, s[10:11]
	global_load_dwordx4 v[0:3], v[32:33], off
	global_load_dwordx4 v[232:235], v[34:35], off
	ds_read_b128 v[4:7], v118
	ds_read_b128 v[236:239], v118 offset:32
	s_waitcnt vmcnt(1) lgkmcnt(1)
	v_mfma_f32_32x32x16_bf16 v[16:31], v[4:7], v[0:3], 0
	ds_read_b128 v[4:7], v118 offset:17408
	ds_read_b128 v[240:243], v118 offset:26112
	s_add_u32 s7, s66, s64
	s_addc_u32 s12, s67, 0
	s_lshl_b64 s[10:11], s[58:59], 1
	s_add_u32 s10, s7, s10
	s_addc_u32 s11, s12, s11
	s_waitcnt vmcnt(0) lgkmcnt(1)
	v_mfma_f32_32x32x16_bf16 v[16:31], v[4:7], v[232:235], v[16:31]
	ds_read_b128 v[4:7], v118 offset:8704
	s_lshl_b32 s7, s6, 1
	s_waitcnt lgkmcnt(0)
	v_mfma_f32_32x32x16_bf16 v[0:15], v[4:7], v[0:3], 0
	v_mfma_f32_32x32x16_bf16 v[0:15], v[240:243], v[232:235], v[0:15]
	global_load_dwordx4 v[232:235], v[32:33], off offset:32
	global_load_dwordx4 v[240:243], v[34:35], off offset:32
	s_waitcnt vmcnt(1)
	v_mfma_f32_32x32x16_bf16 v[16:31], v[236:239], v[232:235], v[16:31]
	ds_read_b128 v[236:239], v118 offset:17440
	s_waitcnt vmcnt(0) lgkmcnt(0)
	v_mfma_f32_32x32x16_bf16 v[16:31], v[236:239], v[240:243], v[16:31]
	ds_read_b128 v[236:239], v118 offset:8736
	s_waitcnt lgkmcnt(0)
	v_mfma_f32_32x32x16_bf16 v[0:15], v[236:239], v[232:235], v[0:15]
	ds_read_b128 v[232:235], v118 offset:26144
	s_waitcnt lgkmcnt(0)
	v_mfma_f32_32x32x16_bf16 v[0:15], v[232:235], v[240:243], v[0:15]
	global_load_dwordx4 v[232:235], v[32:33], off offset:64
	global_load_dwordx4 v[236:239], v[34:35], off offset:64
	ds_read_b128 v[240:243], v118 offset:64
	s_waitcnt vmcnt(1) lgkmcnt(0)
	v_mfma_f32_32x32x16_bf16 v[16:31], v[240:243], v[232:235], v[16:31]
	ds_read_b128 v[240:243], v118 offset:17472
	s_waitcnt vmcnt(0) lgkmcnt(0)
	v_mfma_f32_32x32x16_bf16 v[16:31], v[240:243], v[236:239], v[16:31]
	ds_read_b128 v[240:243], v118 offset:8768
	s_waitcnt lgkmcnt(0)
	v_mfma_f32_32x32x16_bf16 v[0:15], v[240:243], v[232:235], v[0:15]
	ds_read_b128 v[232:235], v118 offset:26176
	s_waitcnt lgkmcnt(0)
	v_mfma_f32_32x32x16_bf16 v[0:15], v[232:235], v[236:239], v[0:15]
	global_load_dwordx4 v[232:235], v[32:33], off offset:96
	global_load_dwordx4 v[236:239], v[34:35], off offset:96
	ds_read_b128 v[240:243], v118 offset:96
	s_waitcnt vmcnt(1) lgkmcnt(0)
	v_mfma_f32_32x32x16_bf16 v[16:31], v[240:243], v[232:235], v[16:31]
	ds_read_b128 v[240:243], v118 offset:17504
	s_waitcnt vmcnt(0) lgkmcnt(0)
	v_mfma_f32_32x32x16_bf16 v[16:31], v[240:243], v[236:239], v[16:31]
	ds_read_b128 v[240:243], v118 offset:8800
	s_waitcnt lgkmcnt(0)
	v_mfma_f32_32x32x16_bf16 v[0:15], v[240:243], v[232:235], v[0:15]
	ds_read_b128 v[232:235], v118 offset:26208
	s_waitcnt lgkmcnt(0)
	v_mfma_f32_32x32x16_bf16 v[0:15], v[232:235], v[236:239], v[0:15]
	global_load_dwordx4 v[232:235], v[32:33], off offset:128
	global_load_dwordx4 v[236:239], v[34:35], off offset:128
	ds_read_b128 v[240:243], v118 offset:128
	s_waitcnt vmcnt(1) lgkmcnt(0)
	v_mfma_f32_32x32x16_bf16 v[16:31], v[240:243], v[232:235], v[16:31]
	ds_read_b128 v[240:243], v118 offset:17536
	s_waitcnt vmcnt(0) lgkmcnt(0)
	v_mfma_f32_32x32x16_bf16 v[16:31], v[240:243], v[236:239], v[16:31]
	ds_read_b128 v[240:243], v118 offset:8832
	s_waitcnt lgkmcnt(0)
	v_mfma_f32_32x32x16_bf16 v[0:15], v[240:243], v[232:235], v[0:15]
	ds_read_b128 v[232:235], v118 offset:26240
	s_waitcnt lgkmcnt(0)
	v_mfma_f32_32x32x16_bf16 v[0:15], v[232:235], v[236:239], v[0:15]
	global_load_dwordx4 v[232:235], v[32:33], off offset:160
	global_load_dwordx4 v[236:239], v[34:35], off offset:160
	ds_read_b128 v[240:243], v118 offset:160
	s_waitcnt vmcnt(1) lgkmcnt(0)
	v_mfma_f32_32x32x16_bf16 v[16:31], v[240:243], v[232:235], v[16:31]
	ds_read_b128 v[240:243], v118 offset:17568
	s_waitcnt vmcnt(0) lgkmcnt(0)
	v_mfma_f32_32x32x16_bf16 v[16:31], v[240:243], v[236:239], v[16:31]
	ds_read_b128 v[240:243], v118 offset:8864
	s_waitcnt lgkmcnt(0)
	v_mfma_f32_32x32x16_bf16 v[0:15], v[240:243], v[232:235], v[0:15]
	ds_read_b128 v[232:235], v118 offset:26272
	s_waitcnt lgkmcnt(0)
	v_mfma_f32_32x32x16_bf16 v[0:15], v[232:235], v[236:239], v[0:15]
	global_load_dwordx4 v[232:235], v[32:33], off offset:192
	global_load_dwordx4 v[236:239], v[34:35], off offset:192
	ds_read_b128 v[240:243], v118 offset:192
	s_waitcnt vmcnt(1) lgkmcnt(0)
	v_mfma_f32_32x32x16_bf16 v[16:31], v[240:243], v[232:235], v[16:31]
	ds_read_b128 v[240:243], v118 offset:17600
	s_waitcnt vmcnt(0) lgkmcnt(0)
	v_mfma_f32_32x32x16_bf16 v[16:31], v[240:243], v[236:239], v[16:31]
	ds_read_b128 v[240:243], v118 offset:8896
	s_waitcnt lgkmcnt(0)
	v_mfma_f32_32x32x16_bf16 v[0:15], v[240:243], v[232:235], v[0:15]
	ds_read_b128 v[232:235], v118 offset:26304
	s_waitcnt lgkmcnt(0)
	v_mfma_f32_32x32x16_bf16 v[0:15], v[232:235], v[236:239], v[0:15]
	global_load_dwordx4 v[232:235], v[32:33], off offset:224
	s_nop 0
	global_load_dwordx4 v[32:35], v[34:35], off offset:224
	ds_read_b128 v[236:239], v118 offset:224
	s_waitcnt vmcnt(1) lgkmcnt(0)
	v_mfma_f32_32x32x16_bf16 v[16:31], v[236:239], v[232:235], v[16:31]
	ds_read_b128 v[236:239], v118 offset:17632
	s_waitcnt vmcnt(0) lgkmcnt(0)
	v_mfma_f32_32x32x16_bf16 v[16:31], v[236:239], v[32:35], v[16:31]
	ds_read_b128 v[236:239], v118 offset:8928
	s_waitcnt lgkmcnt(0)
	v_mfma_f32_32x32x16_bf16 v[0:15], v[236:239], v[232:235], v[0:15]
	ds_read_b128 v[232:235], v118 offset:26336
	s_waitcnt lgkmcnt(0)
	s_barrier
	v_mfma_f32_32x32x16_bf16 v[0:15], v[232:235], v[32:35], v[0:15]
	v_cvt_pk_bf16_f32 v32, v50, s0
	ds_write_b16 v224, v32 offset:34816
	v_cvt_pk_bf16_f32 v32, v51, s0
	ds_write_b16 v224, v32 offset:34960
	v_cvt_pk_bf16_f32 v32, v52, s0
	ds_write_b16 v224, v32 offset:35104
	v_cvt_pk_bf16_f32 v32, v53, s0
	ds_write_b16 v224, v32 offset:35248
	v_cvt_pk_bf16_f32 v32, v54, s0
	ds_write_b16 v224, v32 offset:35968
	v_cvt_pk_bf16_f32 v32, v55, s0
	ds_write_b16 v224, v32 offset:36112
	v_cvt_pk_bf16_f32 v32, v56, s0
	ds_write_b16 v224, v32 offset:36256
	v_cvt_pk_bf16_f32 v32, v57, s0
	ds_write_b16 v224, v32 offset:36400
	v_cvt_pk_bf16_f32 v32, v58, s0
	ds_write_b16 v224, v32 offset:37120
	v_cvt_pk_bf16_f32 v32, v59, s0
	ds_write_b16 v224, v32 offset:37264
	v_cvt_pk_bf16_f32 v32, v60, s0
	ds_write_b16 v224, v32 offset:37408
	v_cvt_pk_bf16_f32 v32, v61, s0
	ds_write_b16 v224, v32 offset:37552
	v_cvt_pk_bf16_f32 v32, v62, s0
	ds_write_b16 v224, v32 offset:38272
	v_cvt_pk_bf16_f32 v32, v63, s0
	ds_write_b16 v224, v32 offset:38416
	v_cvt_pk_bf16_f32 v32, v64, s0
	ds_write_b16 v224, v32 offset:38560
	v_cvt_pk_bf16_f32 v32, v65, s0
	ds_write_b16 v224, v32 offset:38704
	v_lshl_add_u64 v[32:33], s[10:11], 0, v[150:151]
	s_mov_b64 s[10:11], 0x1800000
	v_lshl_add_u64 v[50:51], v[32:33], 0, s[10:11]
	v_lshl_add_u64 v[52:53], v[50:51], 0, v[138:139]
	global_load_dwordx4 v[52:55], v[52:53], off
	s_add_u32 s10, s65, s7
	s_addc_u32 s11, s83, 0
	s_lshl_b64 s[12:13], s[58:59], 11
	s_add_u32 s12, s96, s12
	s_addc_u32 s13, s97, s13
	s_add_u32 s12, s12, s7
	s_addc_u32 s13, s13, 0
	s_lshl_b32 s24, s6, 2
	s_mov_b64 s[6:7], 0x1800
	v_lshl_add_u64 v[56:57], v[50:51], 0, v[140:141]
	global_load_dwordx4 v[56:59], v[56:57], off
	v_lshl_add_u64 v[60:61], v[50:51], 0, v[142:143]
	global_load_dwordx4 v[60:63], v[60:61], off
	v_lshl_add_u64 v[232:233], v[50:51], 0, v[144:145]
	global_load_dwordx4 v[232:235], v[232:233], off
	s_waitcnt vmcnt(0)
	ds_write_b128 v83, v[52:55]
	ds_write_b128 v84, v[56:59]
	ds_write_b128 v85, v[60:63]
	ds_write_b128 v86, v[232:235]
	s_waitcnt lgkmcnt(0)
	s_barrier
	ds_read_b128 v[32:35], v87 offset:53248
	ds_read_b128 v[50:53], v87 offset:53280
	ds_read_b128 v[54:57], v66 offset:34816
	ds_read_b128 v[58:61], v66 offset:34848
	s_waitcnt lgkmcnt(1)
	v_mfma_f32_32x32x16_bf16 v[16:31], v[54:57], v[32:35], v[16:31]
	ds_read_b128 v[54:57], v67 offset:34816
	ds_read_b128 v[62:65], v67 offset:34848
	s_waitcnt lgkmcnt(1)
	v_mfma_f32_32x32x16_bf16 v[0:15], v[54:57], v[32:35], v[0:15]
	v_mfma_f32_32x32x16_bf16 v[16:31], v[58:61], v[50:53], v[16:31]
	v_lshlrev_b32_e32 v60, 1, v38
	v_mov_b32_e32 v61, v155
	s_waitcnt lgkmcnt(0)
	v_mfma_f32_32x32x16_bf16 v[0:15], v[62:65], v[50:53], v[0:15]
	ds_read_b128 v[32:35], v87 offset:53312
	ds_read_b128 v[50:53], v66 offset:34880
	s_waitcnt lgkmcnt(0)
	v_mfma_f32_32x32x16_bf16 v[16:31], v[50:53], v[32:35], v[16:31]
	ds_read_b128 v[50:53], v67 offset:34880
	s_waitcnt lgkmcnt(0)
	v_mfma_f32_32x32x16_bf16 v[0:15], v[50:53], v[32:35], v[0:15]
	ds_read_b128 v[32:35], v87 offset:53344
	ds_read_b128 v[50:53], v66 offset:34912
	s_waitcnt lgkmcnt(0)
	v_mfma_f32_32x32x16_bf16 v[16:31], v[50:53], v[32:35], v[16:31]
	ds_read_b128 v[50:53], v67 offset:34912
	s_waitcnt lgkmcnt(0)
	v_mfma_f32_32x32x16_bf16 v[0:15], v[50:53], v[32:35], v[0:15]
	s_nop 8
	ds_write2_b32 v225, v16, v17 offset1:132
	v_add_u32_e32 v16, 0x400, v225
	ds_write2_b32 v16, v18, v19 offset0:8 offset1:140
	v_add_u32_e32 v16, 0x1000, v225
	ds_write2_b32 v16, v20, v21 offset0:32 offset1:164
	v_add_u32_e32 v16, 0x1400, v225
	ds_write2_b32 v16, v22, v23 offset0:40 offset1:172
	v_add_u32_e32 v16, 0x2000, v225
	ds_write2_b32 v16, v24, v25 offset0:64 offset1:196
	v_add_u32_e32 v16, 0x2400, v225
	ds_write2_b32 v16, v26, v27 offset0:72 offset1:204
	v_add_u32_e32 v16, 0x3000, v225
	ds_write2_b32 v16, v28, v29 offset0:96 offset1:228
	v_add_u32_e32 v16, 0x3400, v225
	ds_write2_b32 v16, v30, v31 offset0:104 offset1:236
	v_add_u32_e32 v16, 0x4200, v225
	ds_write2_b32 v16, v0, v1 offset1:132
	v_add_u32_e32 v0, 0x4600, v225
	ds_write2_b32 v0, v2, v3 offset0:8 offset1:140
	v_add_u32_e32 v0, 0x5200, v225
	ds_write2_b32 v0, v4, v5 offset0:32 offset1:164
	v_add_u32_e32 v0, 0x5600, v225
	ds_write2_b32 v0, v6, v7 offset0:40 offset1:172
	v_add_u32_e32 v0, 0x6200, v225
	ds_write2_b32 v0, v8, v9 offset0:64 offset1:196
	v_add_u32_e32 v0, 0x6600, v225
	ds_write2_b32 v0, v10, v11 offset0:72 offset1:204
	v_add_u32_e32 v0, 0x7200, v225
	ds_write2_b32 v0, v12, v13 offset0:96 offset1:228
	v_add_u32_e32 v0, 0x7600, v225
	ds_write2_b32 v0, v14, v15 offset0:104 offset1:236
	s_waitcnt lgkmcnt(0)
	s_barrier
	ds_read_b128 v[12:15], v88 offset:64
	ds_read_b128 v[8:11], v88 offset:80
	v_lshl_add_u64 v[52:53], v[46:47], 0, s[24:25]
	v_lshl_add_u64 v[50:51], s[12:13], 0, v[42:43]
	v_lshl_add_u64 v[50:51], v[50:51], 0, v[60:61]
	s_waitcnt lgkmcnt(1)
	v_pk_mul_f32 v[4:5], v[12:13], v[12:13]
	s_waitcnt lgkmcnt(0)
	v_pk_mul_f32 v[6:7], v[8:9], v[8:9]
	v_pk_mul_f32 v[0:1], v[14:15], v[14:15]
	v_pk_mul_f32 v[2:3], v[10:11], v[10:11]
	v_mov_b32_e32 v16, v4
	v_mov_b32_e32 v17, v6
	v_mov_b32_e32 v6, v5
	v_pk_add_f32 v[4:5], v[16:17], v[6:7]
	v_mov_b32_e32 v6, v0
	v_mov_b32_e32 v7, v2
	v_pk_add_f32 v[4:5], v[4:5], v[6:7]
	v_mov_b32_e32 v2, v1
	v_pk_add_f32 v[56:57], v[4:5], v[2:3]
	ds_read_b128 v[4:7], v88 offset:96
	ds_read_b128 v[0:3], v88 offset:112
	s_waitcnt lgkmcnt(1)
	v_pk_mul_f32 v[20:21], v[4:5], v[4:5]
	s_waitcnt lgkmcnt(0)
	v_pk_mul_f32 v[22:23], v[0:1], v[0:1]
	v_pk_mul_f32 v[16:17], v[6:7], v[6:7]
	v_pk_mul_f32 v[18:19], v[2:3], v[2:3]
	v_mov_b32_e32 v24, v20
	v_mov_b32_e32 v25, v22
	v_mov_b32_e32 v22, v21
	v_pk_add_f32 v[20:21], v[24:25], v[22:23]
	v_mov_b32_e32 v23, v18
	v_mov_b32_e32 v18, v17
	v_and_b32_e32 v17, 64, v229
	v_mov_b32_e32 v22, v16
	v_xor_b32_e32 v16, 1, v229
	v_add_u32_e32 v17, 64, v17
	v_cmp_lt_i32_e32 vcc, v16, v17
	v_pk_add_f32 v[20:21], v[20:21], v[22:23]
	s_nop 0
	v_cndmask_b32_e32 v16, v229, v16, vcc
	v_lshlrev_b32_e32 v65, 2, v16
	v_xor_b32_e32 v16, 2, v229
	v_cmp_lt_i32_e32 vcc, v16, v17
	v_pk_add_f32 v[58:59], v[20:21], v[18:19]
	s_nop 0
	v_cndmask_b32_e32 v16, v229, v16, vcc
	v_lshlrev_b32_e32 v64, 2, v16
	v_lshl_add_u64 v[16:17], s[10:11], 0, v[40:41]
	v_lshl_add_u64 v[16:17], v[16:17], 0, v[60:61]
	v_lshl_add_u64 v[54:55], v[16:17], 0, s[6:7]
	s_movk_i32 s6, 0x1000
	v_add_co_u32_e32 v16, vcc, s6, v16
	s_nop 1
	v_addc_co_u32_e32 v17, vcc, 0, v17, vcc
	global_load_dwordx2 v[16:17], v[16:17], off offset:2048
	s_waitcnt vmcnt(0)
	v_lshlrev_b32_e32 v62, 16, v17
	v_and_b32_e32 v63, 0xffff0000, v17
	v_mul_f32_e32 v131, 0xbfb8aa3b, v62
	v_exp_f32_e32 v232, v131
	v_mul_f32_e32 v131, 0xbfb8aa3b, v63
	v_exp_f32_e32 v233, v131
	v_lshlrev_b32_e32 v66, 16, v16
	v_and_b32_e32 v67, 0xffff0000, v16
	ds_read_b128 v[28:31], v88
	ds_read_b128 v[24:27], v88 offset:16
	ds_read_b128 v[20:23], v88 offset:32
	ds_read_b128 v[16:19], v88 offset:48
	v_pk_add_f32 v[232:233], v[232:233], 1.0 op_sel_hi:[1,0]
	global_load_dwordx4 v[32:35], v[52:53], off
	v_div_scale_f32 v131, s[6:7], v233, v233, 1.0
	v_rcp_f32_e32 v133, v131
	s_waitcnt lgkmcnt(3)
	v_mov_b32_e32 v236, v29
	s_waitcnt lgkmcnt(2)
	v_mov_b32_e32 v237, v25
	v_mov_b32_e32 v234, v28
	v_fma_f32 v135, -v131, v133, 1.0
	v_fmac_f32_e32 v133, v135, v133
	v_div_scale_f32 v135, vcc, 1.0, v233, 1.0
	v_mul_f32_e32 v137, v135, v133
	v_fma_f32 v139, -v131, v137, v135
	v_fmac_f32_e32 v137, v139, v133
	v_fma_f32 v131, -v131, v137, v135
	v_div_fmas_f32 v131, v131, v133, v137
	v_div_fixup_f32 v233, v131, v233, 1.0
	v_div_scale_f32 v131, s[6:7], v232, v232, 1.0
	v_rcp_f32_e32 v133, v131
	v_mov_b32_e32 v235, v24
	v_pk_mul_f32 v[236:237], v[236:237], v[236:237]
	v_mov_b32_e32 v60, v30
	v_fma_f32 v135, -v131, v133, 1.0
	v_fmac_f32_e32 v133, v135, v133
	v_div_scale_f32 v135, vcc, 1.0, v232, 1.0
	v_mul_f32_e32 v137, v135, v133
	v_fma_f32 v139, -v131, v137, v135
	v_fmac_f32_e32 v137, v139, v133
	v_fma_f32 v131, -v131, v137, v135
	v_div_fmas_f32 v131, v131, v133, v137
	v_div_fixup_f32 v232, v131, v232, 1.0
	v_mul_f32_e32 v131, 0xbfb8aa3b, v66
	v_pk_mul_f32 v[62:63], v[232:233], v[62:63]
	v_exp_f32_e32 v232, v131
	v_mul_f32_e32 v131, 0xbfb8aa3b, v67
	v_exp_f32_e32 v233, v131
	v_mov_b32_e32 v61, v26
	v_pk_fma_f32 v[234:235], v[234:235], v[234:235], v[236:237]
	s_waitcnt lgkmcnt(1)
	v_mov_b32_e32 v238, v21
	v_pk_add_f32 v[232:233], v[232:233], 1.0 op_sel_hi:[1,0]
	s_waitcnt lgkmcnt(0)
	v_mov_b32_e32 v239, v17
	v_div_scale_f32 v131, s[6:7], v233, v233, 1.0
	v_rcp_f32_e32 v133, v131
	v_pk_fma_f32 v[60:61], v[60:61], v[60:61], v[234:235]
	v_mov_b32_e32 v236, v20
	v_mov_b32_e32 v237, v16
	v_fma_f32 v135, -v131, v133, 1.0
	v_fmac_f32_e32 v133, v135, v133
	v_div_scale_f32 v135, vcc, 1.0, v233, 1.0
	v_mul_f32_e32 v137, v135, v133
	v_fma_f32 v139, -v131, v137, v135
	v_fmac_f32_e32 v137, v139, v133
	v_fma_f32 v131, -v131, v137, v135
	v_div_fmas_f32 v131, v131, v133, v137
	v_div_fixup_f32 v233, v131, v233, 1.0
	v_div_scale_f32 v131, s[6:7], v232, v232, 1.0
	v_rcp_f32_e32 v133, v131
	v_pk_mul_f32 v[238:239], v[238:239], v[238:239]
	v_mov_b32_e32 v234, v23
	v_pk_fma_f32 v[236:237], v[236:237], v[236:237], v[238:239]
	v_fma_f32 v135, -v131, v133, 1.0
	v_fmac_f32_e32 v133, v135, v133
	v_div_scale_f32 v135, vcc, 1.0, v232, 1.0
	v_mul_f32_e32 v137, v135, v133
	v_fma_f32 v139, -v131, v137, v135
	v_fmac_f32_e32 v137, v139, v133
	v_fma_f32 v131, -v131, v137, v135
	v_div_fmas_f32 v131, v131, v133, v137
	v_div_fixup_f32 v232, v131, v232, 1.0
	v_pk_mul_f32 v[66:67], v[232:233], v[66:67]
	v_mov_b32_e32 v232, v31
	v_mov_b32_e32 v233, v27
	v_pk_fma_f32 v[60:61], v[232:233], v[232:233], v[60:61]
	v_mov_b32_e32 v232, v22
	v_mov_b32_e32 v233, v18
	v_mov_b32_e32 v235, v19
	v_pk_fma_f32 v[232:233], v[232:233], v[232:233], v[236:237]
	v_add_f32_e32 v60, v60, v61
	v_pk_fma_f32 v[232:233], v[234:235], v[234:235], v[232:233]
	s_nop 0
	v_add_f32_e32 v60, v60, v232
	v_add_f32_e32 v60, v60, v233
	v_add_f32_e32 v56, v60, v56
	v_add_f32_e32 v56, v56, v57
	v_add_f32_e32 v56, v56, v58
	v_add_f32_e32 v56, v56, v59
	ds_bpermute_b32 v57, v65, v56
	s_waitcnt lgkmcnt(0)
	v_add_f32_e32 v56, v56, v57
	ds_bpermute_b32 v57, v64, v56
	s_waitcnt lgkmcnt(0)
	v_add_f32_e32 v56, v56, v57
	v_fmamk_f32 v56, v56, 0x3c000000, v226
	v_cmp_gt_f32_e32 vcc, s44, v56
	v_mul_f32_e32 v57, 0x4b800000, v56
	s_nop 0
	v_cndmask_b32_e32 v56, v56, v57, vcc
	v_rsq_f32_e32 v56, v56
	s_nop 0
	v_mul_f32_e32 v57, 0x45800000, v56
	v_cndmask_b32_e32 v56, v56, v57, vcc
	v_pk_mul_f32 v[28:29], v[28:29], v[56:57] op_sel_hi:[1,0]
	v_pk_mul_f32 v[30:31], v[30:31], v[56:57] op_sel_hi:[1,0]
	s_waitcnt vmcnt(0)
	v_pk_mul_f32 v[28:29], v[32:33], v[28:29]
	v_pk_mul_f32 v[30:31], v[34:35], v[30:31]
	v_pk_mul_f32 v[28:29], v[28:29], v[66:67]
	v_pk_mul_f32 v[30:31], v[30:31], v[62:63]
	v_cvt_pk_bf16_f32 v28, v28, v29
	v_cvt_pk_bf16_f32 v29, v30, v31
	global_store_dwordx2 v[50:51], v[28:29], off offset:1024
	global_load_dwordx4 v[28:31], v[52:53], off offset:16
	s_nop 0
	global_load_dwordx2 v[32:33], v[54:55], off offset:8
	s_waitcnt vmcnt(0)
	v_lshlrev_b32_e32 v34, 16, v32
	v_and_b32_e32 v35, 0xffff0000, v32
	v_mul_f32_e32 v57, 0xbfb8aa3b, v34
	v_exp_f32_e32 v58, v57
	v_mul_f32_e32 v57, 0xbfb8aa3b, v35
	v_exp_f32_e32 v59, v57
	v_lshlrev_b32_e32 v32, 16, v33
	v_and_b32_e32 v33, 0xffff0000, v33
	v_pk_add_f32 v[58:59], v[58:59], 1.0 op_sel_hi:[1,0]
	s_nop 0
	v_div_scale_f32 v57, s[6:7], v59, v59, 1.0
	v_rcp_f32_e32 v60, v57
	s_nop 0
	v_fma_f32 v61, -v57, v60, 1.0
	v_fmac_f32_e32 v60, v61, v60
	v_div_scale_f32 v61, vcc, 1.0, v59, 1.0
	v_mul_f32_e32 v62, v61, v60
	v_fma_f32 v63, -v57, v62, v61
	v_fmac_f32_e32 v62, v63, v60
	v_fma_f32 v57, -v57, v62, v61
	v_div_fmas_f32 v57, v57, v60, v62
	v_div_fixup_f32 v59, v57, v59, 1.0
	v_div_scale_f32 v57, s[6:7], v58, v58, 1.0
	v_rcp_f32_e32 v60, v57
	s_nop 0
	v_fma_f32 v61, -v57, v60, 1.0
	v_fmac_f32_e32 v60, v61, v60
	v_div_scale_f32 v61, vcc, 1.0, v58, 1.0
	v_mul_f32_e32 v62, v61, v60
	v_fma_f32 v63, -v57, v62, v61
	v_fmac_f32_e32 v62, v63, v60
	v_fma_f32 v57, -v57, v62, v61
	v_div_fmas_f32 v57, v57, v60, v62
	v_div_fixup_f32 v58, v57, v58, 1.0
	v_mul_f32_e32 v57, 0xbfb8aa3b, v32
	v_exp_f32_e32 v60, v57
	v_mul_f32_e32 v57, 0xbfb8aa3b, v33
	v_exp_f32_e32 v61, v57
	v_pk_mul_f32 v[34:35], v[58:59], v[34:35]
	v_pk_add_f32 v[60:61], v[60:61], 1.0 op_sel_hi:[1,0]
	s_nop 0
	v_div_scale_f32 v57, s[6:7], v61, v61, 1.0
	v_rcp_f32_e32 v62, v57
	s_nop 0
	v_fma_f32 v63, -v57, v62, 1.0
	v_fmac_f32_e32 v62, v63, v62
	v_div_scale_f32 v63, vcc, 1.0, v61, 1.0
	v_mul_f32_e32 v64, v63, v62
	v_fma_f32 v65, -v57, v64, v63
	v_fmac_f32_e32 v64, v65, v62
	v_fma_f32 v57, -v57, v64, v63
	v_div_fmas_f32 v57, v57, v62, v64
	v_div_fixup_f32 v61, v57, v61, 1.0
	v_div_scale_f32 v57, s[6:7], v60, v60, 1.0
	v_rcp_f32_e32 v62, v57
	s_nop 0
	v_fma_f32 v63, -v57, v62, 1.0
	v_fmac_f32_e32 v62, v63, v62
	v_div_scale_f32 v63, vcc, 1.0, v60, 1.0
	v_mul_f32_e32 v64, v63, v62
	v_fma_f32 v65, -v57, v64, v63
	v_fmac_f32_e32 v64, v65, v62
	v_fma_f32 v57, -v57, v64, v63
	v_div_fmas_f32 v57, v57, v62, v64
	v_div_fixup_f32 v60, v57, v60, 1.0
	v_pk_mul_f32 v[24:25], v[24:25], v[56:57] op_sel_hi:[1,0]
	v_pk_mul_f32 v[26:27], v[26:27], v[56:57] op_sel_hi:[1,0]
	v_pk_mul_f32 v[32:33], v[60:61], v[32:33]
	v_pk_mul_f32 v[24:25], v[28:29], v[24:25]
	v_pk_mul_f32 v[26:27], v[26:27], v[30:31]
	v_pk_mul_f32 v[24:25], v[24:25], v[34:35]
	v_pk_mul_f32 v[26:27], v[26:27], v[32:33]
	v_cvt_pk_bf16_f32 v24, v24, v25
	v_cvt_pk_bf16_f32 v25, v26, v27
	global_store_dwordx2 v[50:51], v[24:25], off offset:1032
	global_load_dwordx4 v[24:27], v[52:53], off offset:32
	s_nop 0
	global_load_dwordx2 v[28:29], v[54:55], off offset:16
	s_waitcnt vmcnt(0)
	v_lshlrev_b32_e32 v30, 16, v28
	v_and_b32_e32 v31, 0xffff0000, v28
	v_mul_f32_e32 v32, 0xbfb8aa3b, v30
	v_mul_f32_e32 v33, 0xbfb8aa3b, v31
	v_exp_f32_e32 v32, v32
	v_exp_f32_e32 v33, v33
	v_lshlrev_b32_e32 v28, 16, v29
	v_and_b32_e32 v29, 0xffff0000, v29
	v_pk_add_f32 v[32:33], v[32:33], 1.0 op_sel_hi:[1,0]
	s_nop 0
	v_div_scale_f32 v34, s[6:7], v33, v33, 1.0
	v_rcp_f32_e32 v35, v34
	s_nop 0
	v_fma_f32 v57, -v34, v35, 1.0
	v_fmac_f32_e32 v35, v57, v35
	v_div_scale_f32 v57, vcc, 1.0, v33, 1.0
	v_mul_f32_e32 v58, v57, v35
	v_fma_f32 v59, -v34, v58, v57
	v_fmac_f32_e32 v58, v59, v35
	v_fma_f32 v34, -v34, v58, v57
	v_div_fmas_f32 v34, v34, v35, v58
	v_div_fixup_f32 v33, v34, v33, 1.0
	v_div_scale_f32 v34, s[6:7], v32, v32, 1.0
	v_rcp_f32_e32 v35, v34
	s_nop 0
	v_fma_f32 v57, -v34, v35, 1.0
	v_fmac_f32_e32 v35, v57, v35
	v_div_scale_f32 v57, vcc, 1.0, v32, 1.0
	v_mul_f32_e32 v58, v57, v35
	v_fma_f32 v59, -v34, v58, v57
	v_fmac_f32_e32 v58, v59, v35
	v_fma_f32 v34, -v34, v58, v57
	v_div_fmas_f32 v34, v34, v35, v58
	v_div_fixup_f32 v32, v34, v32, 1.0
	v_mul_f32_e32 v34, 0xbfb8aa3b, v28
	v_mul_f32_e32 v35, 0xbfb8aa3b, v29
	v_exp_f32_e32 v34, v34
	v_exp_f32_e32 v35, v35
	v_pk_mul_f32 v[30:31], v[32:33], v[30:31]
	v_pk_add_f32 v[34:35], v[34:35], 1.0 op_sel_hi:[1,0]
	s_nop 0
	v_div_scale_f32 v57, s[6:7], v35, v35, 1.0
	v_rcp_f32_e32 v58, v57
	s_nop 0
	v_fma_f32 v59, -v57, v58, 1.0
	v_fmac_f32_e32 v58, v59, v58
	v_div_scale_f32 v59, vcc, 1.0, v35, 1.0
	v_mul_f32_e32 v60, v59, v58
	v_fma_f32 v61, -v57, v60, v59
	v_fmac_f32_e32 v60, v61, v58
	v_fma_f32 v57, -v57, v60, v59
	v_div_fmas_f32 v57, v57, v58, v60
	v_div_fixup_f32 v35, v57, v35, 1.0
	v_div_scale_f32 v57, s[6:7], v34, v34, 1.0
	v_rcp_f32_e32 v58, v57
	s_nop 0
	v_fma_f32 v59, -v57, v58, 1.0
	v_fmac_f32_e32 v58, v59, v58
	v_div_scale_f32 v59, vcc, 1.0, v34, 1.0
	v_mul_f32_e32 v60, v59, v58
	v_fma_f32 v61, -v57, v60, v59
	v_fmac_f32_e32 v60, v61, v58
	v_fma_f32 v57, -v57, v60, v59
	v_div_fmas_f32 v57, v57, v58, v60
	v_div_fixup_f32 v34, v57, v34, 1.0
	v_pk_mul_f32 v[20:21], v[20:21], v[56:57] op_sel_hi:[1,0]
	v_pk_mul_f32 v[22:23], v[22:23], v[56:57] op_sel_hi:[1,0]
	v_pk_mul_f32 v[28:29], v[34:35], v[28:29]
	v_pk_mul_f32 v[20:21], v[20:21], v[24:25]
	v_pk_mul_f32 v[22:23], v[22:23], v[26:27]
	v_pk_mul_f32 v[20:21], v[20:21], v[30:31]
	v_pk_mul_f32 v[22:23], v[22:23], v[28:29]
	v_cvt_pk_bf16_f32 v20, v20, v21
	v_cvt_pk_bf16_f32 v21, v22, v23
	global_store_dwordx2 v[50:51], v[20:21], off offset:1040
	global_load_dwordx4 v[20:23], v[52:53], off offset:48
	s_nop 0
	global_load_dwordx2 v[24:25], v[54:55], off offset:24
	s_waitcnt vmcnt(0)
	v_lshlrev_b32_e32 v26, 16, v24
	v_and_b32_e32 v27, 0xffff0000, v24
	v_mul_f32_e32 v28, 0xbfb8aa3b, v26
	v_mul_f32_e32 v29, 0xbfb8aa3b, v27
	v_exp_f32_e32 v28, v28
	v_exp_f32_e32 v29, v29
	v_lshlrev_b32_e32 v24, 16, v25
	v_and_b32_e32 v25, 0xffff0000, v25
	v_pk_add_f32 v[28:29], v[28:29], 1.0 op_sel_hi:[1,0]
	s_nop 0
	v_div_scale_f32 v30, s[6:7], v29, v29, 1.0
	v_rcp_f32_e32 v31, v30
	s_nop 0
	v_fma_f32 v32, -v30, v31, 1.0
	v_fmac_f32_e32 v31, v32, v31
	v_div_scale_f32 v32, vcc, 1.0, v29, 1.0
	v_mul_f32_e32 v33, v32, v31
	v_fma_f32 v34, -v30, v33, v32
	v_fmac_f32_e32 v33, v34, v31
	v_fma_f32 v30, -v30, v33, v32
	v_div_fmas_f32 v30, v30, v31, v33
	v_div_fixup_f32 v29, v30, v29, 1.0
	v_div_scale_f32 v30, s[6:7], v28, v28, 1.0
	v_rcp_f32_e32 v31, v30
	s_nop 0
	v_fma_f32 v32, -v30, v31, 1.0
	v_fmac_f32_e32 v31, v32, v31
	v_div_scale_f32 v32, vcc, 1.0, v28, 1.0
	v_mul_f32_e32 v33, v32, v31
	v_fma_f32 v34, -v30, v33, v32
	v_fmac_f32_e32 v33, v34, v31
	v_fma_f32 v30, -v30, v33, v32
	v_div_fmas_f32 v30, v30, v31, v33
	v_div_fixup_f32 v28, v30, v28, 1.0
	v_mul_f32_e32 v30, 0xbfb8aa3b, v24
	v_mul_f32_e32 v31, 0xbfb8aa3b, v25
	v_exp_f32_e32 v30, v30
	v_exp_f32_e32 v31, v31
	v_pk_mul_f32 v[26:27], v[28:29], v[26:27]
	v_pk_add_f32 v[30:31], v[30:31], 1.0 op_sel_hi:[1,0]
	s_nop 0
	v_div_scale_f32 v32, s[6:7], v31, v31, 1.0
	v_rcp_f32_e32 v33, v32
	s_nop 0
	v_fma_f32 v34, -v32, v33, 1.0
	v_fmac_f32_e32 v33, v34, v33
	v_div_scale_f32 v34, vcc, 1.0, v31, 1.0
	v_mul_f32_e32 v35, v34, v33
	v_fma_f32 v57, -v32, v35, v34
	v_fmac_f32_e32 v35, v57, v33
	v_fma_f32 v32, -v32, v35, v34
	v_div_fmas_f32 v32, v32, v33, v35
	v_div_fixup_f32 v31, v32, v31, 1.0
	v_div_scale_f32 v32, s[6:7], v30, v30, 1.0
	v_rcp_f32_e32 v33, v32
	s_nop 0
	v_fma_f32 v34, -v32, v33, 1.0
	v_fmac_f32_e32 v33, v34, v33
	v_div_scale_f32 v34, vcc, 1.0, v30, 1.0
	v_mul_f32_e32 v35, v34, v33
	v_fma_f32 v57, -v32, v35, v34
	v_fmac_f32_e32 v35, v57, v33
	v_fma_f32 v32, -v32, v35, v34
	v_div_fmas_f32 v32, v32, v33, v35
	v_div_fixup_f32 v30, v32, v30, 1.0
	v_pk_mul_f32 v[16:17], v[16:17], v[56:57] op_sel_hi:[1,0]
	v_pk_mul_f32 v[18:19], v[18:19], v[56:57] op_sel_hi:[1,0]
	v_pk_mul_f32 v[24:25], v[30:31], v[24:25]
	v_pk_mul_f32 v[16:17], v[16:17], v[20:21]
	v_pk_mul_f32 v[18:19], v[18:19], v[22:23]
	v_pk_mul_f32 v[16:17], v[16:17], v[26:27]
	v_pk_mul_f32 v[18:19], v[18:19], v[24:25]
	v_cvt_pk_bf16_f32 v16, v16, v17
	v_cvt_pk_bf16_f32 v17, v18, v19
	global_store_dwordx2 v[50:51], v[16:17], off offset:1048
	global_load_dwordx2 v[16:17], v[54:55], off offset:32
	v_pk_mul_f32 v[12:13], v[12:13], v[56:57] op_sel_hi:[1,0]
	v_pk_mul_f32 v[14:15], v[14:15], v[56:57] op_sel_hi:[1,0]
	v_pk_mul_f32 v[8:9], v[8:9], v[56:57] op_sel_hi:[1,0]
	v_pk_mul_f32 v[10:11], v[10:11], v[56:57] op_sel_hi:[1,0]
	v_pk_mul_f32 v[4:5], v[4:5], v[56:57] op_sel_hi:[1,0]
	v_pk_mul_f32 v[6:7], v[6:7], v[56:57] op_sel_hi:[1,0]
	v_pk_mul_f32 v[0:1], v[0:1], v[56:57] op_sel_hi:[1,0]
	v_pk_mul_f32 v[2:3], v[2:3], v[56:57] op_sel_hi:[1,0]
	s_waitcnt vmcnt(0)
	v_lshlrev_b32_e32 v22, 16, v16
	v_and_b32_e32 v23, 0xffff0000, v16
	v_lshlrev_b32_e32 v20, 16, v17
	v_and_b32_e32 v21, 0xffff0000, v17
	global_load_dwordx4 v[16:19], v[52:53], off offset:64
	v_mul_f32_e32 v24, 0xbfb8aa3b, v22
	v_mul_f32_e32 v25, 0xbfb8aa3b, v23
	v_exp_f32_e32 v24, v24
	v_exp_f32_e32 v25, v25
	s_waitcnt vmcnt(0)
	v_pk_mul_f32 v[12:13], v[12:13], v[16:17]
	v_pk_add_f32 v[24:25], v[24:25], 1.0 op_sel_hi:[1,0]
	v_mul_f32_e32 v16, 0xbfb8aa3b, v20
	v_div_scale_f32 v26, s[6:7], v25, v25, 1.0
	v_rcp_f32_e32 v27, v26
	v_mul_f32_e32 v17, 0xbfb8aa3b, v21
	v_exp_f32_e32 v16, v16
	v_exp_f32_e32 v17, v17
	v_fma_f32 v28, -v26, v27, 1.0
	v_fmac_f32_e32 v27, v28, v27
	v_div_scale_f32 v28, vcc, 1.0, v25, 1.0
	v_mul_f32_e32 v29, v28, v27
	v_fma_f32 v30, -v26, v29, v28
	v_fmac_f32_e32 v29, v30, v27
	v_fma_f32 v26, -v26, v29, v28
	v_div_fmas_f32 v26, v26, v27, v29
	v_div_fixup_f32 v25, v26, v25, 1.0
	v_div_scale_f32 v26, s[6:7], v24, v24, 1.0
	v_rcp_f32_e32 v27, v26
	v_pk_add_f32 v[16:17], v[16:17], 1.0 op_sel_hi:[1,0]
	v_pk_mul_f32 v[14:15], v[14:15], v[18:19]
	v_fma_f32 v28, -v26, v27, 1.0
	v_fmac_f32_e32 v27, v28, v27
	v_div_scale_f32 v28, vcc, 1.0, v24, 1.0
	v_mul_f32_e32 v29, v28, v27
	v_fma_f32 v30, -v26, v29, v28
	v_fmac_f32_e32 v29, v30, v27
	v_fma_f32 v26, -v26, v29, v28
	v_div_fmas_f32 v26, v26, v27, v29
	v_div_fixup_f32 v24, v26, v24, 1.0
	v_pk_mul_f32 v[22:23], v[24:25], v[22:23]
	s_nop 0
	v_pk_mul_f32 v[12:13], v[12:13], v[22:23]
	v_div_scale_f32 v22, s[6:7], v17, v17, 1.0
	v_rcp_f32_e32 v23, v22
	v_cvt_pk_bf16_f32 v12, v12, v13
	v_fma_f32 v24, -v22, v23, 1.0
	v_fmac_f32_e32 v23, v24, v23
	v_div_scale_f32 v24, vcc, 1.0, v17, 1.0
	v_mul_f32_e32 v25, v24, v23
	v_fma_f32 v26, -v22, v25, v24
	v_fmac_f32_e32 v25, v26, v23
	v_fma_f32 v22, -v22, v25, v24
	v_div_fmas_f32 v22, v22, v23, v25
	v_div_fixup_f32 v17, v22, v17, 1.0
	v_div_scale_f32 v22, s[6:7], v16, v16, 1.0
	v_rcp_f32_e32 v23, v22
	s_nop 0
	v_fma_f32 v24, -v22, v23, 1.0
	v_fmac_f32_e32 v23, v24, v23
	v_div_scale_f32 v24, vcc, 1.0, v16, 1.0
	v_mul_f32_e32 v25, v24, v23
	v_fma_f32 v26, -v22, v25, v24
	v_fmac_f32_e32 v25, v26, v23
	v_fma_f32 v22, -v22, v25, v24
	v_div_fmas_f32 v22, v22, v23, v25
	v_div_fixup_f32 v16, v22, v16, 1.0
	v_pk_mul_f32 v[16:17], v[16:17], v[20:21]
	s_nop 0
	v_pk_mul_f32 v[14:15], v[14:15], v[16:17]
	s_nop 0
	v_cvt_pk_bf16_f32 v13, v14, v15
	global_store_dwordx2 v[50:51], v[12:13], off offset:1056
	global_load_dwordx2 v[12:13], v[54:55], off offset:40
	s_waitcnt vmcnt(0)
	v_lshlrev_b32_e32 v18, 16, v12
	v_and_b32_e32 v19, 0xffff0000, v12
	v_lshlrev_b32_e32 v16, 16, v13
	v_and_b32_e32 v17, 0xffff0000, v13
	global_load_dwordx4 v[12:15], v[52:53], off offset:80
	v_mul_f32_e32 v20, 0xbfb8aa3b, v18
	v_mul_f32_e32 v21, 0xbfb8aa3b, v19
	v_exp_f32_e32 v20, v20
	v_exp_f32_e32 v21, v21
	s_waitcnt vmcnt(0)
	v_pk_mul_f32 v[8:9], v[8:9], v[12:13]
	v_pk_add_f32 v[20:21], v[20:21], 1.0 op_sel_hi:[1,0]
	v_mul_f32_e32 v12, 0xbfb8aa3b, v16
	v_div_scale_f32 v22, s[6:7], v21, v21, 1.0
	v_rcp_f32_e32 v23, v22
	v_mul_f32_e32 v13, 0xbfb8aa3b, v17
	v_exp_f32_e32 v12, v12
	v_exp_f32_e32 v13, v13
	v_fma_f32 v24, -v22, v23, 1.0
	v_fmac_f32_e32 v23, v24, v23
	v_div_scale_f32 v24, vcc, 1.0, v21, 1.0
	v_mul_f32_e32 v25, v24, v23
	v_fma_f32 v26, -v22, v25, v24
	v_fmac_f32_e32 v25, v26, v23
	v_fma_f32 v22, -v22, v25, v24
	v_div_fmas_f32 v22, v22, v23, v25
	v_div_fixup_f32 v21, v22, v21, 1.0
	v_div_scale_f32 v22, s[6:7], v20, v20, 1.0
	v_rcp_f32_e32 v23, v22
	v_pk_add_f32 v[12:13], v[12:13], 1.0 op_sel_hi:[1,0]
	v_pk_mul_f32 v[10:11], v[10:11], v[14:15]
	v_fma_f32 v24, -v22, v23, 1.0
	v_fmac_f32_e32 v23, v24, v23
	v_div_scale_f32 v24, vcc, 1.0, v20, 1.0
	v_mul_f32_e32 v25, v24, v23
	v_fma_f32 v26, -v22, v25, v24
	v_fmac_f32_e32 v25, v26, v23
	v_fma_f32 v22, -v22, v25, v24
	v_div_fmas_f32 v22, v22, v23, v25
	v_div_fixup_f32 v20, v22, v20, 1.0
	v_pk_mul_f32 v[18:19], v[20:21], v[18:19]
	s_nop 0
	v_pk_mul_f32 v[8:9], v[8:9], v[18:19]
	v_div_scale_f32 v18, s[6:7], v13, v13, 1.0
	v_rcp_f32_e32 v19, v18
	v_cvt_pk_bf16_f32 v8, v8, v9
	v_fma_f32 v20, -v18, v19, 1.0
	v_fmac_f32_e32 v19, v20, v19
	v_div_scale_f32 v20, vcc, 1.0, v13, 1.0
	v_mul_f32_e32 v21, v20, v19
	v_fma_f32 v22, -v18, v21, v20
	v_fmac_f32_e32 v21, v22, v19
	v_fma_f32 v18, -v18, v21, v20
	v_div_fmas_f32 v18, v18, v19, v21
	v_div_fixup_f32 v13, v18, v13, 1.0
	v_div_scale_f32 v18, s[6:7], v12, v12, 1.0
	v_rcp_f32_e32 v19, v18
	s_nop 0
	v_fma_f32 v20, -v18, v19, 1.0
	v_fmac_f32_e32 v19, v20, v19
	v_div_scale_f32 v20, vcc, 1.0, v12, 1.0
	v_mul_f32_e32 v21, v20, v19
	v_fma_f32 v22, -v18, v21, v20
	v_fmac_f32_e32 v21, v22, v19
	v_fma_f32 v18, -v18, v21, v20
	v_div_fmas_f32 v18, v18, v19, v21
	v_div_fixup_f32 v12, v18, v12, 1.0
	v_pk_mul_f32 v[12:13], v[12:13], v[16:17]
	s_nop 0
	v_pk_mul_f32 v[10:11], v[10:11], v[12:13]
	s_nop 0
	v_cvt_pk_bf16_f32 v9, v10, v11
	global_store_dwordx2 v[50:51], v[8:9], off offset:1064
	global_load_dwordx2 v[8:9], v[54:55], off offset:48
	s_waitcnt vmcnt(0)
	v_lshlrev_b32_e32 v14, 16, v8
	v_and_b32_e32 v15, 0xffff0000, v8
	v_lshlrev_b32_e32 v12, 16, v9
	v_and_b32_e32 v13, 0xffff0000, v9
	global_load_dwordx4 v[8:11], v[52:53], off offset:96
	v_mul_f32_e32 v16, 0xbfb8aa3b, v14
	v_mul_f32_e32 v17, 0xbfb8aa3b, v15
	v_exp_f32_e32 v16, v16
	v_exp_f32_e32 v17, v17
	s_waitcnt vmcnt(0)
	v_pk_mul_f32 v[4:5], v[4:5], v[8:9]
	v_pk_add_f32 v[16:17], v[16:17], 1.0 op_sel_hi:[1,0]
	v_mul_f32_e32 v8, 0xbfb8aa3b, v12
	v_div_scale_f32 v18, s[6:7], v17, v17, 1.0
	v_rcp_f32_e32 v19, v18
	v_mul_f32_e32 v9, 0xbfb8aa3b, v13
	v_exp_f32_e32 v8, v8
	v_exp_f32_e32 v9, v9
	v_fma_f32 v20, -v18, v19, 1.0
	v_fmac_f32_e32 v19, v20, v19
	v_div_scale_f32 v20, vcc, 1.0, v17, 1.0
	v_mul_f32_e32 v21, v20, v19
	v_fma_f32 v22, -v18, v21, v20
	v_fmac_f32_e32 v21, v22, v19
	v_fma_f32 v18, -v18, v21, v20
	v_div_fmas_f32 v18, v18, v19, v21
	v_div_fixup_f32 v17, v18, v17, 1.0
	v_div_scale_f32 v18, s[6:7], v16, v16, 1.0
	v_rcp_f32_e32 v19, v18
	v_pk_add_f32 v[8:9], v[8:9], 1.0 op_sel_hi:[1,0]
	v_pk_mul_f32 v[6:7], v[6:7], v[10:11]
	v_fma_f32 v20, -v18, v19, 1.0
	v_fmac_f32_e32 v19, v20, v19
	v_div_scale_f32 v20, vcc, 1.0, v16, 1.0
	v_mul_f32_e32 v21, v20, v19
	v_fma_f32 v22, -v18, v21, v20
	v_fmac_f32_e32 v21, v22, v19
	v_fma_f32 v18, -v18, v21, v20
	v_div_fmas_f32 v18, v18, v19, v21
	v_div_fixup_f32 v16, v18, v16, 1.0
	v_pk_mul_f32 v[14:15], v[16:17], v[14:15]
	s_nop 0
	v_pk_mul_f32 v[4:5], v[4:5], v[14:15]
	v_div_scale_f32 v14, s[6:7], v9, v9, 1.0
	v_rcp_f32_e32 v15, v14
	v_cvt_pk_bf16_f32 v4, v4, v5
	v_fma_f32 v16, -v14, v15, 1.0
	v_fmac_f32_e32 v15, v16, v15
	v_div_scale_f32 v16, vcc, 1.0, v9, 1.0
	v_mul_f32_e32 v17, v16, v15
	v_fma_f32 v18, -v14, v17, v16
	v_fmac_f32_e32 v17, v18, v15
	v_fma_f32 v14, -v14, v17, v16
	v_div_fmas_f32 v14, v14, v15, v17
	v_div_fixup_f32 v9, v14, v9, 1.0
	v_div_scale_f32 v14, s[6:7], v8, v8, 1.0
	v_rcp_f32_e32 v15, v14
	s_nop 0
	v_fma_f32 v16, -v14, v15, 1.0
	v_fmac_f32_e32 v15, v16, v15
	v_div_scale_f32 v16, vcc, 1.0, v8, 1.0
	v_mul_f32_e32 v17, v16, v15
	v_fma_f32 v18, -v14, v17, v16
	v_fmac_f32_e32 v17, v18, v15
	v_fma_f32 v14, -v14, v17, v16
	v_div_fmas_f32 v14, v14, v15, v17
	v_div_fixup_f32 v8, v14, v8, 1.0
	v_pk_mul_f32 v[8:9], v[8:9], v[12:13]
	s_nop 0
	v_pk_mul_f32 v[6:7], v[6:7], v[8:9]
	s_nop 0
	v_cvt_pk_bf16_f32 v5, v6, v7
	global_store_dwordx2 v[50:51], v[4:5], off offset:1072
	global_load_dwordx2 v[4:5], v[54:55], off offset:56
	s_waitcnt vmcnt(0)
	v_lshlrev_b32_e32 v8, 16, v4
	v_and_b32_e32 v9, 0xffff0000, v4
	v_lshlrev_b32_e32 v10, 16, v5
	v_and_b32_e32 v11, 0xffff0000, v5
	global_load_dwordx4 v[4:7], v[52:53], off offset:112
	v_mul_f32_e32 v12, 0xbfb8aa3b, v8
	v_mul_f32_e32 v13, 0xbfb8aa3b, v9
	v_exp_f32_e32 v12, v12
	v_exp_f32_e32 v13, v13
	s_waitcnt vmcnt(0)
	v_pk_mul_f32 v[0:1], v[0:1], v[4:5]
	v_pk_add_f32 v[12:13], v[12:13], 1.0 op_sel_hi:[1,0]
	v_mul_f32_e32 v4, 0xbfb8aa3b, v10
	v_div_scale_f32 v14, s[6:7], v13, v13, 1.0
	v_rcp_f32_e32 v15, v14
	v_mul_f32_e32 v5, 0xbfb8aa3b, v11
	v_exp_f32_e32 v4, v4
	v_exp_f32_e32 v5, v5
	v_fma_f32 v16, -v14, v15, 1.0
	v_fmac_f32_e32 v15, v16, v15
	v_div_scale_f32 v16, vcc, 1.0, v13, 1.0
	v_mul_f32_e32 v17, v16, v15
	v_fma_f32 v18, -v14, v17, v16
	v_fmac_f32_e32 v17, v18, v15
	v_fma_f32 v14, -v14, v17, v16
	v_div_fmas_f32 v14, v14, v15, v17
	v_div_fixup_f32 v13, v14, v13, 1.0
	v_div_scale_f32 v14, s[6:7], v12, v12, 1.0
	v_rcp_f32_e32 v15, v14
	v_pk_add_f32 v[4:5], v[4:5], 1.0 op_sel_hi:[1,0]
	v_pk_mul_f32 v[2:3], v[2:3], v[6:7]
	v_fma_f32 v16, -v14, v15, 1.0
	v_fmac_f32_e32 v15, v16, v15
	v_div_scale_f32 v16, vcc, 1.0, v12, 1.0
	v_mul_f32_e32 v17, v16, v15
	v_fma_f32 v18, -v14, v17, v16
	v_fmac_f32_e32 v17, v18, v15
	v_fma_f32 v14, -v14, v17, v16
	v_div_fmas_f32 v14, v14, v15, v17
	v_div_fixup_f32 v12, v14, v12, 1.0
	v_pk_mul_f32 v[8:9], v[12:13], v[8:9]
	s_nop 0
	v_pk_mul_f32 v[0:1], v[0:1], v[8:9]
	v_div_scale_f32 v8, s[6:7], v5, v5, 1.0
	v_rcp_f32_e32 v9, v8
	v_cvt_pk_bf16_f32 v0, v0, v1
	v_fma_f32 v12, -v8, v9, 1.0
	v_fmac_f32_e32 v9, v12, v9
	v_div_scale_f32 v12, vcc, 1.0, v5, 1.0
	v_mul_f32_e32 v13, v12, v9
	v_fma_f32 v14, -v8, v13, v12
	v_fmac_f32_e32 v13, v14, v9
	v_fma_f32 v8, -v8, v13, v12
	v_div_fmas_f32 v8, v8, v9, v13
	v_div_fixup_f32 v5, v8, v5, 1.0
	v_div_scale_f32 v8, s[6:7], v4, v4, 1.0
	v_rcp_f32_e32 v9, v8
	s_nop 0
	v_fma_f32 v12, -v8, v9, 1.0
	v_fmac_f32_e32 v9, v12, v9
	v_div_scale_f32 v12, vcc, 1.0, v4, 1.0
	v_mul_f32_e32 v13, v12, v9
	v_fma_f32 v14, -v8, v13, v12
	v_fmac_f32_e32 v13, v14, v9
	v_fma_f32 v8, -v8, v13, v12
	v_div_fmas_f32 v8, v8, v9, v13
	v_div_fixup_f32 v4, v8, v4, 1.0
	v_pk_mul_f32 v[4:5], v[4:5], v[10:11]
	s_nop 0
	v_pk_mul_f32 v[2:3], v[2:3], v[4:5]
	s_nop 0
	v_cvt_pk_bf16_f32 v1, v2, v3
	global_store_dwordx2 v[50:51], v[0:1], off offset:1080
	s_barrier
	s_branch .LBB0_752
.LBB0_757:
	s_and_b64 vcc, exec, s[6:7]
	s_cbranch_vccz .LBB0_752
	s_lshl_b32 s6, s20, 8
	s_add_u32 s82, s65, s6
	s_addc_u32 s83, s83, 0
	v_lshl_add_u64 v[4:5], s[82:83], 0, v[154:155]
	v_mov_b32_e32 v131, v155
	v_lshl_add_u64 v[6:7], v[4:5], 0, v[130:131]
	global_load_dwordx4 v[12:15], v[6:7], off
	v_mov_b32_e32 v133, v155
	v_lshl_add_u64 v[8:9], v[4:5], 0, v[132:133]
	v_mov_b32_e32 v135, v155
	v_lshl_add_u64 v[10:11], v[4:5], 0, v[134:135]
	v_mov_b32_e32 v137, v155
	v_lshl_add_u64 v[4:5], v[4:5], 0, v[136:137]
	s_add_u32 s10, s66, s64
	s_addc_u32 s11, s67, 0
	s_lshl_b64 s[6:7], s[58:59], 1
	s_add_u32 s6, s10, s6
	s_addc_u32 s7, s11, s7
	v_mov_b32_e32 v151, v155
	v_mov_b32_e32 v139, v155
	v_mov_b32_e32 v141, v155
	v_mov_b32_e32 v143, v155
	v_mov_b32_e32 v145, v155
	global_load_dwordx4 v[16:19], v[8:9], off
	global_load_dwordx4 v[20:23], v[10:11], off
	global_load_dwordx4 v[24:27], v[4:5], off
	global_load_dwordx4 v[28:31], v[6:7], off offset:1024
	global_load_dwordx4 v[32:35], v[8:9], off offset:1024
	global_load_dwordx4 v[52:55], v[10:11], off offset:1024
	global_load_dwordx4 v[56:59], v[4:5], off offset:1024
	v_lshl_add_u64 v[0:1], s[6:7], 0, v[150:151]
	s_mov_b64 s[6:7], 0xc00000
	v_lshl_add_u64 v[4:5], v[0:1], 0, s[6:7]
	v_lshl_add_u64 v[60:61], v[4:5], 0, v[138:139]
	global_load_dwordx4 v[60:63], v[60:61], off
	v_lshl_add_u64 v[64:65], v[4:5], 0, v[140:141]
	global_load_dwordx4 v[64:67], v[64:65], off
	v_lshl_add_u64 v[232:233], v[4:5], 0, v[142:143]
	global_load_dwordx4 v[232:235], v[232:233], off
	v_lshl_add_u64 v[236:237], v[4:5], 0, v[144:145]
	global_load_dwordx4 v[236:239], v[236:237], off
	s_waitcnt vmcnt(0)
	ds_write_b128 v170, v[12:15]
	ds_write_b128 v171, v[16:19]
	ds_write_b128 v172, v[20:23]
	ds_write_b128 v173, v[24:27]
	ds_write_b128 v75, v[28:31]
	ds_write_b128 v76, v[32:35]
	ds_write_b128 v77, v[52:55]
	ds_write_b128 v78, v[56:59]
	ds_write_b128 v89, v[60:63]
	ds_write_b128 v90, v[64:67]
	ds_write_b128 v91, v[232:235]
	ds_write_b128 v92, v[236:239]
	s_mov_b64 s[84:85], exec
	v_readlane_b32 s6, v250, 58
	v_readlane_b32 s7, v250, 59
	s_and_b64 s[6:7], s[84:85], s[6:7]
	s_mov_b64 exec, s[6:7]
	s_cbranch_execz .LBB0_760
	v_or_b32_e32 v0, s58, v128
	v_ashrrev_i32_e32 v1, 31, v0
	v_lshlrev_b64 v[0:1], 6, v[0:1]
	v_lshl_add_u64 v[0:1], s[76:77], 0, v[0:1]
	s_lshl_b32 s24, s20, 2
	v_lshl_add_u64 v[0:1], v[0:1], 0, s[24:25]
	global_load_dword v3, v[0:1], off
	global_load_dword v2, v[0:1], off offset:16
	global_load_dword v4, v[0:1], off offset:32
	s_mov_b32 s7, 0xb2a5705f
	s_mov_b32 s10, 0x42ce8ed0
	s_mov_b32 s11, 0xc2b17218
	s_mov_b32 s12, 0x3f2aaaab
	s_mov_b32 s13, 0x3f317218
	s_mov_b32 s6, 0x7f800000
	s_mov_b32 s15, 0x33800000
	v_readlane_b32 s36, v249, 2
	v_readlane_b32 s37, v249, 3
	v_readlane_b32 s38, v249, 4
	v_readlane_b32 s39, v249, 5
	v_readlane_b32 s40, v249, 6
	v_readlane_b32 s41, v249, 7
	s_ashr_i32 s81, s80, 31
	s_mov_b32 s24, 0x3fb8aa3b
	s_mov_b32 s42, 0xc2ce8ed0
	s_mov_b32 s43, 0x42b17218
	s_mov_b32 s28, 0x3fb8aa3b
	s_mov_b32 s22, 0x42b17218
	s_waitcnt vmcnt(0)
	v_max_f32_e32 v5, v4, v4
	v_min_f32_e32 v6, 0, v5
	v_mul_f32_e64 v5, |v4|, s21
	v_fma_f32 v7, |v4|, s21, -v5
	v_rndne_f32_e32 v8, v5
	v_fma_f32 v7, |v4|, s7, v7
	v_sub_f32_e32 v5, v5, v8
	v_add_f32_e32 v5, v5, v7
	v_exp_f32_e32 v5, v5
	v_cvt_i32_f32_e32 v7, v8
	v_cmp_ngt_f32_e64 vcc, |v4|, s10
	v_ldexp_f32 v5, v5, v7
	s_nop 0
	v_cndmask_b32_e32 v5, 0, v5, vcc
	v_cmp_nlt_f32_e64 vcc, |v4|, s11
	s_nop 1
	v_cndmask_b32_e32 v7, v228, v5, vcc
	v_add_f32_e32 v8, 1.0, v7
	v_add_f32_e32 v4, -1.0, v8
	v_sub_f32_e32 v5, v4, v8
	v_add_f32_e32 v5, 1.0, v5
	v_sub_f32_e32 v4, v7, v4
	v_add_f32_e32 v9, v4, v5
	v_frexp_mant_f32_e32 v4, v8
	v_cmp_gt_f32_e32 vcc, s12, v4
	v_cvt_f64_f32_e32 v[4:5], v8
	v_frexp_exp_i32_f64_e32 v4, v[4:5]
	v_subbrev_co_u32_e32 v4, vcc, 0, v4, vcc
	v_sub_u32_e32 v5, 0, v4
	v_ldexp_f32 v8, v8, v5
	v_ldexp_f32 v5, v9, v5
	v_add_f32_e32 v9, -1.0, v8
	v_add_f32_e32 v10, 1.0, v9
	v_sub_f32_e32 v10, v8, v10
	v_add_f32_e32 v10, v5, v10
	v_add_f32_e32 v11, v9, v10
	v_sub_f32_e32 v9, v9, v11
	v_add_f32_e32 v9, v10, v9
	v_add_f32_e32 v10, 1.0, v8
	v_add_f32_e32 v12, -1.0, v10
	v_sub_f32_e32 v8, v8, v12
	v_add_f32_e32 v5, v5, v8
	v_add_f32_e32 v8, v10, v5
	v_sub_f32_e32 v10, v10, v8
	v_add_f32_e32 v5, v5, v10
	v_rcp_f32_e32 v10, v8
	v_cvt_f32_i32_e32 v4, v4
	v_cmp_neq_f32_e32 vcc, s6, v7
	v_mul_f32_e32 v12, v11, v10
	v_mul_f32_e32 v13, v8, v12
	v_fma_f32 v14, v12, v8, -v13
	v_fmac_f32_e32 v14, v12, v5
	v_add_f32_e32 v15, v13, v14
	v_sub_f32_e32 v16, v11, v15
	v_sub_f32_e32 v11, v11, v16
	v_sub_f32_e32 v13, v15, v13
	v_sub_f32_e32 v11, v11, v15
	v_add_f32_e32 v9, v9, v11
	v_sub_f32_e32 v11, v13, v14
	v_add_f32_e32 v9, v11, v9
	v_add_f32_e32 v11, v16, v9
	v_mul_f32_e32 v13, v10, v11
	v_mul_f32_e32 v14, v8, v13
	v_fma_f32 v8, v13, v8, -v14
	v_fmac_f32_e32 v8, v13, v5
	v_sub_f32_e32 v5, v16, v11
	v_add_f32_e32 v5, v9, v5
	v_add_f32_e32 v9, v14, v8
	v_sub_f32_e32 v15, v11, v9
	v_sub_f32_e32 v11, v11, v15
	v_sub_f32_e32 v14, v9, v14
	v_sub_f32_e32 v9, v11, v9
	v_add_f32_e32 v5, v5, v9
	v_sub_f32_e32 v8, v14, v8
	v_add_f32_e32 v5, v8, v5
	v_add_f32_e32 v8, v12, v13
	v_add_f32_e32 v5, v15, v5
	v_sub_f32_e32 v9, v8, v12
	v_mul_f32_e32 v5, v10, v5
	v_sub_f32_e32 v9, v13, v9
	v_add_f32_e32 v5, v9, v5
	v_mul_f32_e32 v12, 0x3f317218, v4
	v_add_f32_e32 v9, v8, v5
	v_fma_f32 v13, v4, s13, -v12
	v_mul_f32_e32 v10, v9, v9
	v_fmac_f32_e32 v13, 0xb102e308, v4
	v_sub_f32_e32 v4, v9, v8
	v_fmamk_f32 v11, v10, 0x3e9b6dac, v227
	v_sub_f32_e32 v4, v5, v4
	v_add_f32_e32 v5, v12, v13
	v_fmaak_f32 v11, v10, v11, 0x3f2aaada
	v_sub_f32_e32 v8, v5, v12
	v_ldexp_f32 v12, v9, 1
	v_mul_f32_e32 v9, v9, v10
	v_mul_f32_e32 v9, v9, v11
	v_add_f32_e32 v10, v12, v9
	v_sub_f32_e32 v11, v10, v12
	v_ldexp_f32 v4, v4, 1
	v_sub_f32_e32 v9, v9, v11
	v_add_f32_e32 v4, v4, v9
	v_add_f32_e32 v9, v10, v4
	v_sub_f32_e32 v10, v9, v10
	v_sub_f32_e32 v4, v4, v10
	v_add_f32_e32 v10, v5, v9
	v_sub_f32_e32 v11, v10, v5
	v_sub_f32_e32 v12, v10, v11
	v_sub_f32_e32 v8, v13, v8
	v_sub_f32_e32 v5, v5, v12
	v_sub_f32_e32 v9, v9, v11
	v_add_f32_e32 v5, v9, v5
	v_add_f32_e32 v9, v8, v4
	v_sub_f32_e32 v11, v9, v8
	v_sub_f32_e32 v12, v9, v11
	v_sub_f32_e32 v8, v8, v12
	v_sub_f32_e32 v4, v4, v11
	v_add_f32_e32 v5, v9, v5
	v_add_f32_e32 v4, v4, v8
	v_add_f32_e32 v8, v10, v5
	v_sub_f32_e32 v9, v8, v10
	v_sub_f32_e32 v5, v5, v9
	v_add_f32_e32 v4, v4, v5
	global_load_dword v5, v[0:1], off offset:48
	v_add_f32_e32 v4, v8, v4
	v_cndmask_b32_e32 v4, v228, v4, vcc
	v_cmp_lt_f32_e64 vcc, |v7|, s15
	s_waitcnt vmcnt(0)
	v_mul_f32_e64 v0, |v5|, s21
	v_cndmask_b32_e32 v4, v4, v7, vcc
	v_sub_f32_e32 v4, v6, v4
	v_fma_f32 v1, |v5|, s21, -v0
	v_rndne_f32_e32 v6, v0
	v_fma_f32 v1, |v5|, s7, v1
	v_sub_f32_e32 v0, v0, v6
	v_add_f32_e32 v0, v0, v1
	v_exp_f32_e32 v0, v0
	v_cvt_i32_f32_e32 v1, v6
	v_cmp_ngt_f32_e64 vcc, |v5|, s10
	v_ldexp_f32 v0, v0, v1
	s_nop 0
	v_cndmask_b32_e32 v0, 0, v0, vcc
	v_cmp_nlt_f32_e64 vcc, |v5|, s11
	v_readlane_b32 s10, v250, 62
	v_readlane_b32 s11, v250, 63
	v_cndmask_b32_e32 v6, v228, v0, vcc
	v_add_f32_e32 v7, 1.0, v6
	v_add_f32_e32 v0, -1.0, v7
	v_sub_f32_e32 v1, v0, v7
	v_add_f32_e32 v1, 1.0, v1
	v_sub_f32_e32 v0, v6, v0
	v_add_f32_e32 v8, v0, v1
	v_frexp_mant_f32_e32 v0, v7
	v_cmp_gt_f32_e32 vcc, s12, v0
	v_cvt_f64_f32_e32 v[0:1], v7
	v_frexp_exp_i32_f64_e32 v0, v[0:1]
	v_subbrev_co_u32_e32 v0, vcc, 0, v0, vcc
	v_sub_u32_e32 v1, 0, v0
	v_ldexp_f32 v7, v7, v1
	v_ldexp_f32 v1, v8, v1
	v_add_f32_e32 v8, -1.0, v7
	v_add_f32_e32 v9, 1.0, v8
	v_sub_f32_e32 v9, v7, v9
	v_add_f32_e32 v9, v1, v9
	v_add_f32_e32 v10, v8, v9
	v_sub_f32_e32 v8, v8, v10
	v_add_f32_e32 v8, v9, v8
	v_add_f32_e32 v9, 1.0, v7
	v_add_f32_e32 v11, -1.0, v9
	v_sub_f32_e32 v7, v7, v11
	v_add_f32_e32 v1, v1, v7
	v_add_f32_e32 v7, v9, v1
	v_sub_f32_e32 v9, v9, v7
	v_add_f32_e32 v1, v1, v9
	v_rcp_f32_e32 v9, v7
	v_cvt_f32_i32_e32 v0, v0
	v_cmp_neq_f32_e32 vcc, s6, v6
	v_readlane_b32 s6, v250, 60
	v_mul_f32_e32 v11, v10, v9
	v_mul_f32_e32 v12, v7, v11
	v_fma_f32 v13, v11, v7, -v12
	v_fmac_f32_e32 v13, v11, v1
	v_add_f32_e32 v14, v12, v13
	v_sub_f32_e32 v15, v10, v14
	v_sub_f32_e32 v10, v10, v15
	v_sub_f32_e32 v12, v14, v12
	v_sub_f32_e32 v10, v10, v14
	v_add_f32_e32 v8, v8, v10
	v_sub_f32_e32 v10, v12, v13
	v_add_f32_e32 v8, v10, v8
	v_add_f32_e32 v10, v15, v8
	v_mul_f32_e32 v12, v9, v10
	v_mul_f32_e32 v13, v7, v12
	v_fma_f32 v7, v12, v7, -v13
	v_fmac_f32_e32 v7, v12, v1
	v_sub_f32_e32 v1, v15, v10
	v_add_f32_e32 v1, v8, v1
	v_add_f32_e32 v8, v13, v7
	v_sub_f32_e32 v14, v10, v8
	v_sub_f32_e32 v10, v10, v14
	v_sub_f32_e32 v13, v8, v13
	v_sub_f32_e32 v8, v10, v8
	v_add_f32_e32 v1, v1, v8
	v_sub_f32_e32 v7, v13, v7
	v_add_f32_e32 v1, v7, v1
	v_add_f32_e32 v7, v11, v12
	v_add_f32_e32 v1, v14, v1
	v_sub_f32_e32 v8, v7, v11
	v_mul_f32_e32 v1, v9, v1
	v_sub_f32_e32 v8, v12, v8
	v_add_f32_e32 v1, v8, v1
	v_mul_f32_e32 v11, 0x3f317218, v0
	v_add_f32_e32 v8, v7, v1
	v_fma_f32 v12, v0, s13, -v11
	v_mul_f32_e32 v9, v8, v8
	v_fmac_f32_e32 v12, 0xb102e308, v0
	v_sub_f32_e32 v0, v8, v7
	v_fmamk_f32 v10, v9, 0x3e9b6dac, v227
	v_sub_f32_e32 v0, v1, v0
	v_add_f32_e32 v1, v11, v12
	v_fmaak_f32 v10, v9, v10, 0x3f2aaada
	v_sub_f32_e32 v7, v1, v11
	v_ldexp_f32 v11, v8, 1
	v_mul_f32_e32 v8, v8, v9
	v_mul_f32_e32 v8, v8, v10
	v_add_f32_e32 v9, v11, v8
	v_sub_f32_e32 v10, v9, v11
	v_ldexp_f32 v0, v0, 1
	v_sub_f32_e32 v8, v8, v10
	v_add_f32_e32 v0, v0, v8
	v_add_f32_e32 v8, v9, v0
	v_sub_f32_e32 v9, v8, v9
	v_sub_f32_e32 v0, v0, v9
	v_add_f32_e32 v9, v1, v8
	v_sub_f32_e32 v10, v9, v1
	v_sub_f32_e32 v11, v9, v10
	v_sub_f32_e32 v7, v12, v7
	v_sub_f32_e32 v1, v1, v11
	v_sub_f32_e32 v8, v8, v10
	v_add_f32_e32 v1, v8, v1
	v_add_f32_e32 v8, v7, v0
	v_sub_f32_e32 v10, v8, v7
	v_sub_f32_e32 v11, v8, v10
	v_sub_f32_e32 v7, v7, v11
	v_sub_f32_e32 v0, v0, v10
	v_add_f32_e32 v1, v8, v1
	v_add_f32_e32 v0, v0, v7
	v_add_f32_e32 v7, v9, v1
	v_sub_f32_e32 v8, v7, v9
	v_sub_f32_e32 v1, v1, v8
	v_add_f32_e32 v0, v0, v1
	v_add_f32_e32 v0, v7, v0
	v_cndmask_b32_e32 v0, v228, v0, vcc
	v_cmp_lt_f32_e64 vcc, |v6|, s15
	v_and_b32_e32 v1, 64, v229
	v_readlane_b32 s7, v250, 61
	v_cndmask_b32_e32 v0, v0, v6, vcc
	v_add_u32_e32 v6, -1, v229
	v_cmp_lt_i32_e32 vcc, v6, v1
	v_readlane_b32 s12, v249, 0
	v_readlane_b32 s13, v249, 1
	v_cndmask_b32_e32 v6, v6, v229, vcc
	v_lshlrev_b32_e32 v6, 2, v6
	ds_bpermute_b32 v7, v6, v4
	v_max_f32_e32 v5, v5, v5
	s_mov_b32 s15, 0xc2ce8ed0
	s_waitcnt lgkmcnt(0)
	v_add_f32_e32 v7, v4, v7
	v_cndmask_b32_e64 v4, v7, v4, s[6:7]
	v_add_u32_e32 v7, -2, v229
	v_cmp_lt_i32_e32 vcc, v7, v1
	s_nop 1
	v_cndmask_b32_e32 v7, v7, v229, vcc
	v_lshlrev_b32_e32 v7, 2, v7
	ds_bpermute_b32 v8, v7, v4
	s_waitcnt lgkmcnt(0)
	v_add_f32_e32 v8, v4, v8
	v_cndmask_b32_e64 v4, v8, v4, s[10:11]
	v_add_u32_e32 v8, -4, v229
	v_cmp_lt_i32_e32 vcc, v8, v1
	s_nop 1
	v_cndmask_b32_e32 v8, v8, v229, vcc
	v_lshlrev_b32_e32 v8, 2, v8
	ds_bpermute_b32 v9, v8, v4
	s_waitcnt lgkmcnt(0)
	v_add_f32_e32 v9, v4, v9
	v_cndmask_b32_e64 v4, v9, v4, s[12:13]
	v_add_u32_e32 v9, -8, v229
	v_cmp_lt_i32_e32 vcc, v9, v1
	s_nop 1
	v_cndmask_b32_e32 v9, v9, v229, vcc
	v_lshlrev_b32_e32 v9, 2, v9
	ds_bpermute_b32 v10, v9, v4
	s_waitcnt lgkmcnt(0)
	v_add_f32_e32 v10, v4, v10
	v_cndmask_b32_e64 v4, v10, v4, s[36:37]
	v_add_u32_e32 v10, -16, v229
	v_cmp_lt_i32_e32 vcc, v10, v1
	s_nop 1
	v_cndmask_b32_e32 v10, v10, v229, vcc
	v_lshlrev_b32_e32 v10, 2, v10
	ds_bpermute_b32 v11, v10, v4
	s_waitcnt lgkmcnt(0)
	v_add_f32_e32 v11, v4, v11
	v_cndmask_b32_e64 v4, v11, v4, s[38:39]
	v_subrev_u32_e32 v11, 32, v229
	v_cmp_lt_i32_e32 vcc, v11, v1
	s_nop 1
	v_cndmask_b32_e32 v1, v11, v229, vcc
	v_lshlrev_b32_e32 v1, 2, v1
	ds_bpermute_b32 v11, v1, v4
	s_waitcnt lgkmcnt(0)
	v_add_f32_e32 v11, v4, v11
	v_cndmask_b32_e64 v4, v11, v4, s[40:41]
	v_min_f32_e32 v11, 0, v5
	v_sub_f32_e32 v5, v3, v4
	ds_bpermute_b32 v3, v6, v5
	s_waitcnt lgkmcnt(0)
	v_max_f32_e32 v3, v3, v3
	v_max_f32_e32 v3, v5, v3
	v_cndmask_b32_e64 v3, v3, v5, s[6:7]
	ds_bpermute_b32 v6, v7, v3
	s_lshl_b64 s[6:7], s[80:81], 2
	s_add_u32 s6, s8, s6
	s_addc_u32 s7, s9, s7
	s_waitcnt lgkmcnt(0)
	v_max_f32_e32 v6, v6, v6
	v_max_f32_e32 v6, v3, v6
	v_cndmask_b32_e64 v3, v6, v3, s[10:11]
	ds_bpermute_b32 v6, v8, v3
	v_readlane_b32 s10, v249, 10
	v_readlane_b32 s11, v249, 11
	s_waitcnt lgkmcnt(0)
	v_max_f32_e32 v6, v6, v6
	v_max_f32_e32 v6, v3, v6
	v_cndmask_b32_e64 v3, v6, v3, s[12:13]
	ds_bpermute_b32 v6, v9, v3
	v_readlane_b32 s12, v249, 12
	v_readlane_b32 s13, v249, 13
	s_waitcnt lgkmcnt(0)
	v_max_f32_e32 v6, v6, v6
	v_max_f32_e32 v6, v3, v6
	v_cndmask_b32_e64 v3, v6, v3, s[36:37]
	ds_bpermute_b32 v6, v10, v3
	v_readlane_b32 s36, v249, 14
	v_readlane_b32 s37, v249, 15
	s_waitcnt lgkmcnt(0)
	v_max_f32_e32 v6, v6, v6
	v_max_f32_e32 v6, v3, v6
	v_cndmask_b32_e64 v3, v6, v3, s[38:39]
	ds_bpermute_b32 v1, v1, v3
	v_max_f32_e32 v6, v3, v3
	v_readlane_b32 s38, v249, 16
	v_readlane_b32 s39, v249, 17
	s_waitcnt lgkmcnt(0)
	v_max_f32_e32 v1, v1, v1
	v_max_f32_e32 v1, v6, v1
	v_cndmask_b32_e64 v6, v1, v3, s[40:41]
	v_sub_f32_e32 v3, v11, v0
	global_load_dwordx2 v[0:1], v155, s[6:7]
	v_add_f32_e32 v6, v4, v6
	v_readlane_b32 s6, v249, 8
	v_readlane_b32 s7, v249, 9
	s_waitcnt vmcnt(0)
	v_add_f32_e32 v0, v0, v4
	v_max_f32_e32 v6, v0, v6
	v_sub_f32_e32 v4, v4, v6
	v_sub_f32_e32 v0, v0, v6
	ds_write_b32 v93, v4
	ds_write_b32 v94, v5
	v_mul_f32_e32 v4, 0x3fb8aa3b, v0
	v_fma_f32 v5, v0, s24, -v4
	v_rndne_f32_e32 v7, v4
	v_fmac_f32_e32 v5, 0x32a5705f, v0
	v_sub_f32_e32 v4, v4, v7
	v_add_f32_e32 v4, v4, v5
	v_exp_f32_e32 v4, v4
	v_cvt_i32_f32_e32 v5, v7
	v_cmp_ngt_f32_e32 vcc, s42, v0
	v_ldexp_f32 v4, v4, v5
	s_nop 0
	v_cndmask_b32_e32 v4, 0, v4, vcc
	v_cmp_nlt_f32_e32 vcc, s43, v0
	s_nop 1
	v_cndmask_b32_e32 v0, v228, v4, vcc
	ds_write_b32 v95, v0
	ds_write_b32 v96, v6
	v_and_b32_e32 v0, 63, v229
	v_cmp_ne_u32_e32 vcc, 63, v0
	s_nop 1
	v_addc_co_u32_e32 v4, vcc, 0, v229, vcc
	v_lshlrev_b32_e32 v4, 2, v4
	ds_bpermute_b32 v5, v4, v3
	v_cmp_gt_u32_e32 vcc, 62, v0
	s_waitcnt lgkmcnt(0)
	v_add_f32_e32 v5, v3, v5
	v_cndmask_b32_e64 v3, v5, v3, s[6:7]
	v_cndmask_b32_e64 v5, 0, 2, vcc
	v_add_lshl_u32 v5, v5, v229, 2
	ds_bpermute_b32 v6, v5, v3
	v_cmp_gt_u32_e32 vcc, 60, v0
	s_waitcnt lgkmcnt(0)
	v_add_f32_e32 v6, v3, v6
	v_cndmask_b32_e64 v3, v3, v6, s[10:11]
	v_cndmask_b32_e64 v6, 0, 4, vcc
	v_add_lshl_u32 v6, v6, v229, 2
	ds_bpermute_b32 v7, v6, v3
	v_cmp_gt_u32_e32 vcc, 56, v0
	s_waitcnt lgkmcnt(0)
	v_add_f32_e32 v7, v3, v7
	v_cndmask_b32_e64 v3, v3, v7, s[12:13]
	v_cndmask_b32_e64 v7, 0, 8, vcc
	v_add_lshl_u32 v7, v7, v229, 2
	ds_bpermute_b32 v8, v7, v3
	v_cmp_gt_u32_e32 vcc, 48, v0
	s_waitcnt lgkmcnt(0)
	v_add_f32_e32 v8, v3, v8
	v_cndmask_b32_e64 v0, 0, 16, vcc
	v_cndmask_b32_e64 v3, v3, v8, s[36:37]
	v_add_lshl_u32 v0, v0, v229, 2
	ds_bpermute_b32 v8, v0, v3
	s_waitcnt lgkmcnt(0)
	v_add_f32_e32 v8, v3, v8
	v_cndmask_b32_e64 v3, v3, v8, s[38:39]
	v_lshl_or_b32 v8, v229, 2, v230
	ds_bpermute_b32 v9, v8, v3
	s_waitcnt lgkmcnt(0)
	v_add_f32_e32 v9, v3, v9
	v_cndmask_b32_e64 v3, v3, v9, s[40:41]
	v_sub_f32_e32 v2, v2, v3
	ds_bpermute_b32 v4, v4, v2
	v_add_f32_e32 v1, v1, v3
	s_waitcnt lgkmcnt(0)
	v_max_f32_e32 v4, v4, v4
	v_max_f32_e32 v4, v2, v4
	v_cndmask_b32_e64 v4, v4, v2, s[6:7]
	ds_bpermute_b32 v5, v5, v4
	s_waitcnt lgkmcnt(0)
	v_max_f32_e32 v5, v5, v5
	v_max_f32_e32 v5, v4, v5
	v_cndmask_b32_e64 v4, v4, v5, s[10:11]
	ds_bpermute_b32 v5, v6, v4
	s_waitcnt lgkmcnt(0)
	v_max_f32_e32 v5, v5, v5
	v_max_f32_e32 v5, v4, v5
	v_cndmask_b32_e64 v4, v4, v5, s[12:13]
	ds_bpermute_b32 v5, v7, v4
	s_waitcnt lgkmcnt(0)
	v_max_f32_e32 v5, v5, v5
	v_max_f32_e32 v5, v4, v5
	v_cndmask_b32_e64 v4, v4, v5, s[36:37]
	ds_bpermute_b32 v0, v0, v4
	s_waitcnt lgkmcnt(0)
	v_max_f32_e32 v0, v0, v0
	v_max_f32_e32 v0, v4, v0
	v_cndmask_b32_e64 v0, v4, v0, s[38:39]
	ds_bpermute_b32 v4, v8, v0
	v_max_f32_e32 v5, v0, v0
	s_waitcnt lgkmcnt(0)
	v_max_f32_e32 v4, v4, v4
	v_max_f32_e32 v4, v5, v4
	v_cndmask_b32_e64 v0, v0, v4, s[40:41]
	v_add_f32_e32 v0, v3, v0
	v_max_f32_e32 v0, v1, v0
	v_sub_f32_e32 v3, v3, v0
	v_sub_f32_e32 v1, v1, v0
	ds_write_b32 v97, v3
	ds_write_b32 v98, v2
	v_mul_f32_e32 v2, 0x3fb8aa3b, v1
	v_fma_f32 v3, v1, s24, -v2
	v_rndne_f32_e32 v4, v2
	v_fmac_f32_e32 v3, 0x32a5705f, v1
	v_sub_f32_e32 v2, v2, v4
	v_add_f32_e32 v2, v2, v3
	v_exp_f32_e32 v2, v2
	v_cvt_i32_f32_e32 v3, v4
	v_cmp_ngt_f32_e32 vcc, s42, v1
	v_ldexp_f32 v2, v2, v3
	s_nop 0
	v_cndmask_b32_e32 v2, 0, v2, vcc
	v_cmp_nlt_f32_e32 vcc, s43, v1
	s_nop 1
	v_cndmask_b32_e32 v1, v228, v2, vcc
	ds_write_b32 v99, v1
	ds_write_b32 v100, v0

.LBB0_1780:
	s_or_b64 exec, exec, s[2:3]
	v_readlane_b32 s2, v250, 56
	s_add_u32 s6, s90, 0xc971900
	v_readlane_b32 s3, v250, 57
	s_addc_u32 s7, s91, 0
	s_and_b64 vcc, exec, s[2:3]
	s_waitcnt lgkmcnt(0)
	s_barrier
	s_cbranch_vccz .LBB0_1818
	v_mov_b32_e32 v1, 0
	global_load_dwordx2 v[2:3], v1, s[76:77]
	v_lshrrev_b32_e32 v6, 7, v128
	s_movk_i32 s2, 0x110
	v_mul_u32_u24_e32 v4, 0x90, v183
	s_movk_i32 s3, 0x380
	v_lshlrev_b32_e32 v7, 8, v128
	s_movk_i32 s8, 0x4000
	v_mbcnt_hi_u32_b32 v8, -1, v182
	v_readlane_b32 s44, v250, 28
	v_bfe_u32 v5, v128, 6, 1
	v_lshlrev_b32_e32 v0, 2, v190
	v_lshl_add_u32 v167, v129, 1, v4
	v_lshlrev_b32_e32 v4, 6, v6
	v_mad_u32_u24 v168, v194, s2, v154
	v_and_or_b32 v169, v128, s3, v158
	v_cmp_eq_u32_e64 s[2:3], 1, v6
	v_and_or_b32 v171, v7, s8, v197
	v_or_b32_e32 v6, 0x3f00, v7
	v_readlane_b32 s56, v250, 40
	v_readlane_b32 s57, v250, 41
	v_and_b32_e32 v7, 64, v8
	s_add_u32 s40, s90, 0x362a180
	v_lshl_or_b32 v170, v5, 14, v197
	v_add_u32_e32 v160, 0x12000, v0
	v_and_b32_e32 v161, 0x7f, v128
	v_lshlrev_b32_e32 v161, 2, v161
	global_load_dword v252, v161, s[56:57]
	v_add_u32_e32 v161, 0x12000, v161
	s_waitcnt vmcnt(0)
	ds_write_b32 v161, v252
	s_waitcnt lgkmcnt(0)
	v_xor_b32_e32 v0, 32, v8
	v_lshl_or_b32 v172, v5, 5, v192
	v_add_u32_e32 v5, 64, v7
	s_addc_u32 s42, s91, 0
	v_cmp_lt_i32_e32 vcc, v0, v5
	v_readlane_b32 s46, v250, 30
	v_readlane_b32 s47, v250, 31
	s_add_u32 s43, s90, 0x352e100
	v_cndmask_b32_e32 v0, v8, v0, vcc
	s_mov_b32 s9, 0
	v_mov_b32_e32 v166, 0x358637bd
	s_mov_b32 s41, 0x800000
	v_mov_b32_e32 v163, v1
	v_mov_b32_e32 v159, v1
	v_mov_b32_e32 v155, v1
	v_mov_b32_e32 v151, v1
	v_lshlrev_b32_e32 v162, 1, v4
	v_add_u32_e32 v173, v197, v6
	s_addc_u32 s46, s91, 0
	v_lshlrev_b32_e32 v174, 2, v0
	s_mov_b32 s47, s33
	v_readlane_b32 s45, v250, 29
	v_readlane_b32 s48, v250, 32
	v_readlane_b32 s49, v250, 33
	v_readlane_b32 s50, v250, 34
	v_readlane_b32 s51, v250, 35
	v_readlane_b32 s52, v250, 36
	v_readlane_b32 s53, v250, 37
	v_readlane_b32 s54, v250, 38
	v_readlane_b32 s55, v250, 39
	v_readlane_b32 s58, v250, 42
	v_readlane_b32 s59, v250, 43
	s_waitcnt vmcnt(0)
	v_cndmask_b32_e64 v175, v2, 1.0, s[4:5]
	v_sub_f32_e32 v176, 1.0, v3
	s_branch .LBB0_1783

.LBB0_1816:
	s_or_b64 exec, exec, s[12:13]
	s_waitcnt lgkmcnt(0)
	s_barrier
	s_and_saveexec_b64 s[12:13], s[4:5]
	s_cbranch_execz .LBB0_1782
	ds_read2st64_b32 v[10:11], v171 offset1:1
	ds_read2st64_b32 v[2:3], v171 offset0:2 offset1:3
	ds_read2st64_b32 v[12:13], v171 offset0:4 offset1:5
	ds_read2st64_b32 v[14:15], v171 offset0:6 offset1:7
	ds_read2st64_b32 v[80:81], v171 offset0:8 offset1:9
	ds_read2st64_b32 v[82:83], v171 offset0:10 offset1:11
	ds_read2st64_b32 v[84:85], v171 offset0:12 offset1:13
	ds_read2st64_b32 v[86:87], v171 offset0:14 offset1:15
	ds_read2st64_b32 v[88:89], v171 offset0:16 offset1:17
	ds_read2st64_b32 v[90:91], v171 offset0:18 offset1:19
	ds_read2st64_b32 v[92:93], v171 offset0:20 offset1:21
	ds_read2st64_b32 v[94:95], v171 offset0:22 offset1:23
	ds_read2st64_b32 v[96:97], v171 offset0:24 offset1:25
	ds_read2st64_b32 v[98:99], v171 offset0:26 offset1:27
	ds_read2st64_b32 v[100:101], v171 offset0:28 offset1:29
	ds_read2st64_b32 v[102:103], v171 offset0:30 offset1:31
	ds_read2st64_b32 v[104:105], v171 offset0:32 offset1:33
	ds_read2st64_b32 v[106:107], v171 offset0:34 offset1:35
	ds_read2st64_b32 v[108:109], v171 offset0:36 offset1:37
	ds_read2st64_b32 v[110:111], v171 offset0:38 offset1:39
	ds_read2st64_b32 v[112:113], v171 offset0:40 offset1:41
	ds_read2st64_b32 v[114:115], v171 offset0:42 offset1:43
	ds_read2st64_b32 v[116:117], v171 offset0:44 offset1:45
	ds_read2st64_b32 v[118:119], v171 offset0:46 offset1:47
	ds_read2st64_b32 v[120:121], v171 offset0:56 offset1:57
	ds_read2st64_b32 v[122:123], v171 offset0:58 offset1:59
	ds_read2st64_b32 v[4:5], v171 offset0:60 offset1:61
	ds_read_b32 v8, v171 offset:15872
	ds_read_b32 v9, v173
	ds_read2st64_b32 v[124:125], v171 offset0:48 offset1:49
	ds_read2st64_b32 v[126:127], v171 offset0:50 offset1:51
	ds_read2st64_b32 v[128:129], v171 offset0:52 offset1:53
	ds_read2st64_b32 v[130:131], v171 offset0:54 offset1:55
	s_waitcnt lgkmcnt(14)
	v_pk_fma_f32 v[138:139], v[64:65], v[0:1], v[10:11] op_sel_hi:[1,0,1] neg_lo:[0,0,1] neg_hi:[0,0,1]
	v_pk_fma_f32 v[66:67], v[66:67], v[0:1], v[2:3] op_sel_hi:[1,0,1] neg_lo:[0,0,1] neg_hi:[0,0,1]
	v_pk_mul_f32 v[140:141], v[138:139], v[138:139]
	s_waitcnt lgkmcnt(6)
	v_pk_fma_f32 v[6:7], v[28:29], v[0:1], v[4:5] op_sel_hi:[1,0,1] neg_lo:[0,0,1] neg_hi:[0,0,1]
	s_waitcnt lgkmcnt(4)
	v_pk_fma_f32 v[8:9], v[30:31], v[0:1], v[8:9] op_sel_hi:[1,0,1] neg_lo:[0,0,1] neg_hi:[0,0,1]
	v_pk_mul_f32 v[136:137], v[66:67], v[66:67]
	v_pk_fma_f32 v[70:71], v[70:71], v[0:1], v[14:15] op_sel_hi:[1,0,1] neg_lo:[0,0,1] neg_hi:[0,0,1]
	v_pk_fma_f32 v[144:145], v[68:69], v[0:1], v[12:13] op_sel_hi:[1,0,1] neg_lo:[0,0,1] neg_hi:[0,0,1]
	v_pk_fma_f32 v[74:75], v[74:75], v[0:1], v[82:83] op_sel_hi:[1,0,1] neg_lo:[0,0,1] neg_hi:[0,0,1]
	v_pk_fma_f32 v[72:73], v[72:73], v[0:1], v[80:81] op_sel_hi:[1,0,1] neg_lo:[0,0,1] neg_hi:[0,0,1]
	v_pk_fma_f32 v[68:69], v[78:79], v[0:1], v[86:87] op_sel_hi:[1,0,1] neg_lo:[0,0,1] neg_hi:[0,0,1]
	v_pk_fma_f32 v[76:77], v[76:77], v[0:1], v[84:85] op_sel_hi:[1,0,1] neg_lo:[0,0,1] neg_hi:[0,0,1]
	v_pk_fma_f32 v[64:65], v[50:51], v[0:1], v[90:91] op_sel_hi:[1,0,1] neg_lo:[0,0,1] neg_hi:[0,0,1]
	v_pk_fma_f32 v[88:89], v[48:49], v[0:1], v[88:89] op_sel_hi:[1,0,1] neg_lo:[0,0,1] neg_hi:[0,0,1]
	v_pk_fma_f32 v[54:55], v[54:55], v[0:1], v[94:95] op_sel_hi:[1,0,1] neg_lo:[0,0,1] neg_hi:[0,0,1]
	v_pk_fma_f32 v[92:93], v[52:53], v[0:1], v[92:93] op_sel_hi:[1,0,1] neg_lo:[0,0,1] neg_hi:[0,0,1]
	v_pk_fma_f32 v[50:51], v[58:59], v[0:1], v[98:99] op_sel_hi:[1,0,1] neg_lo:[0,0,1] neg_hi:[0,0,1]
	v_pk_fma_f32 v[96:97], v[56:57], v[0:1], v[96:97] op_sel_hi:[1,0,1] neg_lo:[0,0,1] neg_hi:[0,0,1]
	v_pk_fma_f32 v[48:49], v[62:63], v[0:1], v[102:103] op_sel_hi:[1,0,1] neg_lo:[0,0,1] neg_hi:[0,0,1]
	v_pk_fma_f32 v[60:61], v[60:61], v[0:1], v[100:101] op_sel_hi:[1,0,1] neg_lo:[0,0,1] neg_hi:[0,0,1]
	v_pk_fma_f32 v[34:35], v[34:35], v[0:1], v[106:107] op_sel_hi:[1,0,1] neg_lo:[0,0,1] neg_hi:[0,0,1]
	v_pk_fma_f32 v[56:57], v[32:33], v[0:1], v[104:105] op_sel_hi:[1,0,1] neg_lo:[0,0,1] neg_hi:[0,0,1]
	v_pk_fma_f32 v[32:33], v[38:39], v[0:1], v[110:111] op_sel_hi:[1,0,1] neg_lo:[0,0,1] neg_hi:[0,0,1]
	v_pk_fma_f32 v[52:53], v[36:37], v[0:1], v[108:109] op_sel_hi:[1,0,1] neg_lo:[0,0,1] neg_hi:[0,0,1]
	v_pk_fma_f32 v[30:31], v[42:43], v[0:1], v[114:115] op_sel_hi:[1,0,1] neg_lo:[0,0,1] neg_hi:[0,0,1]
	v_pk_fma_f32 v[40:41], v[40:41], v[0:1], v[112:113] op_sel_hi:[1,0,1] neg_lo:[0,0,1] neg_hi:[0,0,1]
	v_pk_fma_f32 v[28:29], v[46:47], v[0:1], v[118:119] op_sel_hi:[1,0,1] neg_lo:[0,0,1] neg_hi:[0,0,1]
	v_pk_fma_f32 v[38:39], v[44:45], v[0:1], v[116:117] op_sel_hi:[1,0,1] neg_lo:[0,0,1] neg_hi:[0,0,1]
	s_waitcnt lgkmcnt(2)
	v_pk_fma_f32 v[14:15], v[18:19], v[0:1], v[126:127] op_sel_hi:[1,0,1] neg_lo:[0,0,1] neg_hi:[0,0,1]
	v_pk_fma_f32 v[36:37], v[16:17], v[0:1], v[124:125] op_sel_hi:[1,0,1] neg_lo:[0,0,1] neg_hi:[0,0,1]
	s_waitcnt lgkmcnt(0)
	v_pk_fma_f32 v[12:13], v[22:23], v[0:1], v[130:131] op_sel_hi:[1,0,1] neg_lo:[0,0,1] neg_hi:[0,0,1]
	v_pk_fma_f32 v[18:19], v[20:21], v[0:1], v[128:129] op_sel_hi:[1,0,1] neg_lo:[0,0,1] neg_hi:[0,0,1]
	v_pk_fma_f32 v[10:11], v[26:27], v[0:1], v[122:123] op_sel_hi:[1,0,1] neg_lo:[0,0,1] neg_hi:[0,0,1]
	v_pk_fma_f32 v[16:17], v[24:25], v[0:1], v[120:121] op_sel_hi:[1,0,1] neg_lo:[0,0,1] neg_hi:[0,0,1]
	v_add_f32_e32 v0, v140, v141
	v_add_f32_e32 v0, v0, v136
	v_pk_mul_f32 v[146:147], v[144:145], v[144:145]
	v_add_f32_e32 v0, v0, v137
	v_add_f32_e32 v0, v0, v146
	v_pk_mul_f32 v[142:143], v[70:71], v[70:71]
	v_add_f32_e32 v0, v0, v147
	v_add_f32_e32 v0, v0, v142
	v_pk_mul_f32 v[80:81], v[72:73], v[72:73]
	v_add_f32_e32 v0, v0, v143
	v_add_f32_e32 v0, v0, v80
	v_pk_mul_f32 v[82:83], v[74:75], v[74:75]
	v_add_f32_e32 v0, v0, v81
	v_add_f32_e32 v0, v0, v82
	v_pk_mul_f32 v[84:85], v[76:77], v[76:77]
	v_add_f32_e32 v0, v0, v83
	v_add_f32_e32 v0, v0, v84
	v_pk_mul_f32 v[78:79], v[68:69], v[68:69]
	v_add_f32_e32 v0, v0, v85
	v_add_f32_e32 v0, v0, v78
	v_pk_mul_f32 v[90:91], v[88:89], v[88:89]
	v_add_f32_e32 v0, v0, v79
	v_add_f32_e32 v0, v0, v90
	v_pk_mul_f32 v[86:87], v[64:65], v[64:65]
	v_add_f32_e32 v0, v0, v91
	v_add_f32_e32 v0, v0, v86
	v_pk_mul_f32 v[178:179], v[92:93], v[92:93]
	v_add_f32_e32 v0, v0, v87
	v_add_f32_e32 v0, v0, v178
	v_pk_mul_f32 v[94:95], v[54:55], v[54:55]
	v_add_f32_e32 v0, v0, v179
	v_add_f32_e32 v0, v0, v94
	v_pk_mul_f32 v[98:99], v[96:97], v[96:97]
	v_add_f32_e32 v0, v0, v95
	v_add_f32_e32 v0, v0, v98
	v_pk_mul_f32 v[58:59], v[50:51], v[50:51]
	v_add_f32_e32 v0, v0, v99
	v_add_f32_e32 v0, v0, v58
	v_pk_mul_f32 v[100:101], v[60:61], v[60:61]
	v_add_f32_e32 v0, v0, v59
	v_add_f32_e32 v0, v0, v100
	v_pk_mul_f32 v[62:63], v[48:49], v[48:49]
	v_add_f32_e32 v0, v0, v101
	v_add_f32_e32 v0, v0, v62
	v_pk_mul_f32 v[104:105], v[56:57], v[56:57]
	v_add_f32_e32 v0, v0, v63
	v_add_f32_e32 v0, v0, v104
	v_pk_mul_f32 v[102:103], v[34:35], v[34:35]
	v_add_f32_e32 v0, v0, v105
	v_add_f32_e32 v0, v0, v102
	v_pk_mul_f32 v[108:109], v[52:53], v[52:53]
	v_add_f32_e32 v0, v0, v103
	v_add_f32_e32 v0, v0, v108
	v_pk_mul_f32 v[106:107], v[32:33], v[32:33]
	v_add_f32_e32 v0, v0, v109
	v_add_f32_e32 v0, v0, v106
	v_pk_mul_f32 v[110:111], v[40:41], v[40:41]
	v_add_f32_e32 v0, v0, v107
	v_add_f32_e32 v0, v0, v110
	v_pk_mul_f32 v[42:43], v[30:31], v[30:31]
	v_add_f32_e32 v0, v0, v111
	v_add_f32_e32 v0, v0, v42
	v_pk_mul_f32 v[44:45], v[38:39], v[38:39]
	v_add_f32_e32 v0, v0, v43
	v_add_f32_e32 v0, v0, v44
	v_pk_mul_f32 v[46:47], v[28:29], v[28:29]
	v_add_f32_e32 v0, v0, v45
	v_add_f32_e32 v0, v0, v46
	v_pk_mul_f32 v[114:115], v[36:37], v[36:37]
	v_add_f32_e32 v0, v0, v47
	v_add_f32_e32 v0, v0, v114
	v_pk_mul_f32 v[112:113], v[14:15], v[14:15]
	v_add_f32_e32 v0, v0, v115
	v_add_f32_e32 v0, v0, v112
	v_pk_mul_f32 v[20:21], v[18:19], v[18:19]
	v_add_f32_e32 v0, v0, v113
	v_add_f32_e32 v0, v0, v20
	v_pk_mul_f32 v[22:23], v[12:13], v[12:13]
	v_add_f32_e32 v0, v0, v21
	v_add_f32_e32 v0, v0, v22
	v_pk_mul_f32 v[24:25], v[16:17], v[16:17]
	v_add_f32_e32 v0, v0, v23
	v_add_f32_e32 v0, v0, v24
	v_pk_mul_f32 v[26:27], v[10:11], v[10:11]
	v_add_f32_e32 v0, v0, v25
	v_add_f32_e32 v0, v0, v26
	v_pk_mul_f32 v[132:133], v[6:7], v[6:7]
	v_add_f32_e32 v0, v0, v27
	v_add_f32_e32 v0, v0, v132
	v_pk_mul_f32 v[134:135], v[8:9], v[8:9]
	v_add_f32_e32 v0, v0, v133
	v_add_f32_e32 v0, v0, v134
	v_add_f32_e32 v0, v0, v135
	ds_bpermute_b32 v22, v174, v0
	v_lshl_add_u64 v[20:21], v[164:165], 1, s[6:7]
	s_mov_b32 s11, s9
	v_lshl_add_u64 v[20:21], v[20:21], 0, s[10:11]
	v_mov_b32_e32 v157, v1
	s_waitcnt lgkmcnt(0)
	ds_read_b128 v[2:5], v160
	v_add_f32_e32 v0, v0, v22
	v_fmamk_f32 v0, v0, 0x3c000000, v166
	v_mul_f32_e32 v22, 0x4b800000, v0
	v_cmp_gt_f32_e32 vcc, s41, v0
	v_lshl_add_u64 v[20:21], v[20:21], 0, v[156:157]
	s_nop 0
	v_cndmask_b32_e32 v0, v0, v22, vcc
	v_rsq_f32_e32 v0, v0
	s_nop 0
	v_mul_f32_e32 v22, 0x45800000, v0
	v_cndmask_b32_e32 v0, v0, v22, vcc
	v_mul_f32_e32 v0, v176, v0
	v_pk_mul_f32 v[22:23], v[138:139], v[0:1] op_sel_hi:[1,0]
	v_pk_mul_f32 v[24:25], v[74:75], v[0:1] op_sel_hi:[1,0]
	s_waitcnt lgkmcnt(0)
	v_pk_mul_f32 v[2:3], v[2:3], v[22:23]
	v_pk_mul_f32 v[22:23], v[66:67], v[0:1] op_sel_hi:[1,0]
	v_cvt_pk_bf16_f32 v2, v2, v3
	v_pk_mul_f32 v[4:5], v[4:5], v[22:23]
	v_pk_mul_f32 v[22:23], v[144:145], v[0:1] op_sel_hi:[1,0]
	v_cvt_pk_bf16_f32 v3, v4, v5
	global_store_dwordx2 v[20:21], v[2:3], off
	ds_read_b128 v[2:5], v160 offset:32
	v_pk_mul_f32 v[14:15], v[14:15], v[0:1] op_sel_hi:[1,0]
	v_pk_mul_f32 v[12:13], v[12:13], v[0:1] op_sel_hi:[1,0]
	v_pk_mul_f32 v[10:11], v[10:11], v[0:1] op_sel_hi:[1,0]
	v_pk_mul_f32 v[6:7], v[6:7], v[0:1] op_sel_hi:[1,0]
	v_pk_mul_f32 v[8:9], v[8:9], v[0:1] op_sel_hi:[1,0]
	s_waitcnt lgkmcnt(0)
	v_pk_mul_f32 v[2:3], v[2:3], v[22:23]
	v_pk_mul_f32 v[22:23], v[70:71], v[0:1] op_sel_hi:[1,0]
	v_cvt_pk_bf16_f32 v2, v2, v3
	v_pk_mul_f32 v[4:5], v[4:5], v[22:23]
	v_pk_mul_f32 v[22:23], v[72:73], v[0:1] op_sel_hi:[1,0]
	v_cvt_pk_bf16_f32 v3, v4, v5
	global_store_dwordx2 v[20:21], v[2:3], off offset:16
	ds_read_b128 v[2:5], v160 offset:64
	s_waitcnt lgkmcnt(0)
	v_pk_mul_f32 v[2:3], v[2:3], v[22:23]
	v_pk_mul_f32 v[4:5], v[24:25], v[4:5]
	v_cvt_pk_bf16_f32 v2, v2, v3
	v_cvt_pk_bf16_f32 v3, v4, v5
	global_store_dwordx2 v[20:21], v[2:3], off offset:32
	ds_read_b128 v[2:5], v160 offset:96
	v_pk_mul_f32 v[22:23], v[76:77], v[0:1] op_sel_hi:[1,0]
	v_pk_mul_f32 v[24:25], v[68:69], v[0:1] op_sel_hi:[1,0]
	s_waitcnt lgkmcnt(0)
	v_pk_mul_f32 v[2:3], v[22:23], v[2:3]
	v_pk_mul_f32 v[4:5], v[24:25], v[4:5]
	v_cvt_pk_bf16_f32 v2, v2, v3
	v_cvt_pk_bf16_f32 v3, v4, v5
	global_store_dwordx2 v[20:21], v[2:3], off offset:48
	ds_read_b128 v[2:5], v160 offset:128
	v_pk_mul_f32 v[22:23], v[88:89], v[0:1] op_sel_hi:[1,0]
	v_pk_mul_f32 v[24:25], v[64:65], v[0:1] op_sel_hi:[1,0]
	s_waitcnt lgkmcnt(0)
	v_pk_mul_f32 v[2:3], v[22:23], v[2:3]
	v_pk_mul_f32 v[4:5], v[24:25], v[4:5]
	v_cvt_pk_bf16_f32 v2, v2, v3
	v_cvt_pk_bf16_f32 v3, v4, v5
	global_store_dwordx2 v[20:21], v[2:3], off offset:64
	ds_read_b128 v[2:5], v160 offset:160
	v_pk_mul_f32 v[22:23], v[92:93], v[0:1] op_sel_hi:[1,0]
	v_pk_mul_f32 v[24:25], v[54:55], v[0:1] op_sel_hi:[1,0]
	s_waitcnt lgkmcnt(0)
	v_pk_mul_f32 v[2:3], v[22:23], v[2:3]
	v_pk_mul_f32 v[4:5], v[24:25], v[4:5]
	v_cvt_pk_bf16_f32 v2, v2, v3
	v_cvt_pk_bf16_f32 v3, v4, v5
	global_store_dwordx2 v[20:21], v[2:3], off offset:80
	ds_read_b128 v[2:5], v160 offset:192
	v_pk_mul_f32 v[22:23], v[96:97], v[0:1] op_sel_hi:[1,0]
	v_pk_mul_f32 v[24:25], v[50:51], v[0:1] op_sel_hi:[1,0]
	s_waitcnt lgkmcnt(0)
	v_pk_mul_f32 v[2:3], v[22:23], v[2:3]
	v_pk_mul_f32 v[4:5], v[24:25], v[4:5]
	v_cvt_pk_bf16_f32 v2, v2, v3
	v_cvt_pk_bf16_f32 v3, v4, v5
	global_store_dwordx2 v[20:21], v[2:3], off offset:96
	ds_read_b128 v[2:5], v160 offset:224
	v_pk_mul_f32 v[22:23], v[60:61], v[0:1] op_sel_hi:[1,0]
	v_pk_mul_f32 v[24:25], v[48:49], v[0:1] op_sel_hi:[1,0]
	s_waitcnt lgkmcnt(0)
	v_pk_mul_f32 v[2:3], v[22:23], v[2:3]
	v_pk_mul_f32 v[4:5], v[24:25], v[4:5]
	v_cvt_pk_bf16_f32 v2, v2, v3
	v_cvt_pk_bf16_f32 v3, v4, v5
	global_store_dwordx2 v[20:21], v[2:3], off offset:112
	ds_read_b128 v[2:5], v160 offset:256
	v_pk_mul_f32 v[22:23], v[56:57], v[0:1] op_sel_hi:[1,0]
	v_pk_mul_f32 v[24:25], v[34:35], v[0:1] op_sel_hi:[1,0]
	s_waitcnt lgkmcnt(0)
	v_pk_mul_f32 v[2:3], v[22:23], v[2:3]
	v_pk_mul_f32 v[4:5], v[24:25], v[4:5]
	v_cvt_pk_bf16_f32 v2, v2, v3
	v_cvt_pk_bf16_f32 v3, v4, v5
	global_store_dwordx2 v[20:21], v[2:3], off offset:128
	ds_read_b128 v[2:5], v160 offset:288
	v_pk_mul_f32 v[22:23], v[52:53], v[0:1] op_sel_hi:[1,0]
	v_pk_mul_f32 v[24:25], v[32:33], v[0:1] op_sel_hi:[1,0]
	s_waitcnt lgkmcnt(0)
	v_pk_mul_f32 v[2:3], v[22:23], v[2:3]
	v_pk_mul_f32 v[4:5], v[24:25], v[4:5]
	v_cvt_pk_bf16_f32 v2, v2, v3
	v_cvt_pk_bf16_f32 v3, v4, v5
	global_store_dwordx2 v[20:21], v[2:3], off offset:144
	ds_read_b128 v[2:5], v160 offset:320
	v_pk_mul_f32 v[22:23], v[40:41], v[0:1] op_sel_hi:[1,0]
	v_pk_mul_f32 v[24:25], v[30:31], v[0:1] op_sel_hi:[1,0]
	s_waitcnt lgkmcnt(0)
	v_pk_mul_f32 v[2:3], v[22:23], v[2:3]
	v_pk_mul_f32 v[4:5], v[24:25], v[4:5]
	v_cvt_pk_bf16_f32 v2, v2, v3
	v_cvt_pk_bf16_f32 v3, v4, v5
	global_store_dwordx2 v[20:21], v[2:3], off offset:160
	ds_read_b128 v[2:5], v160 offset:352
	v_pk_mul_f32 v[22:23], v[38:39], v[0:1] op_sel_hi:[1,0]
	v_pk_mul_f32 v[24:25], v[28:29], v[0:1] op_sel_hi:[1,0]
	s_waitcnt lgkmcnt(0)
	v_pk_mul_f32 v[2:3], v[22:23], v[2:3]
	v_pk_mul_f32 v[4:5], v[24:25], v[4:5]
	v_cvt_pk_bf16_f32 v2, v2, v3
	v_cvt_pk_bf16_f32 v3, v4, v5
	global_store_dwordx2 v[20:21], v[2:3], off offset:176
	ds_read_b128 v[2:5], v160 offset:384
	v_pk_mul_f32 v[22:23], v[36:37], v[0:1] op_sel_hi:[1,0]
	s_waitcnt lgkmcnt(0)
	v_pk_mul_f32 v[4:5], v[14:15], v[4:5]
	v_pk_mul_f32 v[2:3], v[22:23], v[2:3]
	v_pk_mul_f32 v[14:15], v[18:19], v[0:1] op_sel_hi:[1,0]
	v_cvt_pk_bf16_f32 v2, v2, v3
	v_cvt_pk_bf16_f32 v3, v4, v5
	global_store_dwordx2 v[20:21], v[2:3], off offset:192
	ds_read_b128 v[2:5], v160 offset:416
	s_waitcnt lgkmcnt(0)
	v_pk_mul_f32 v[2:3], v[14:15], v[2:3]
	v_pk_mul_f32 v[4:5], v[12:13], v[4:5]
	v_cvt_pk_bf16_f32 v2, v2, v3
	v_cvt_pk_bf16_f32 v3, v4, v5
	global_store_dwordx2 v[20:21], v[2:3], off offset:208
	ds_read_b128 v[2:5], v160 offset:448
	v_pk_mul_f32 v[12:13], v[16:17], v[0:1] op_sel_hi:[1,0]
	s_waitcnt lgkmcnt(0)
	v_pk_mul_f32 v[4:5], v[10:11], v[4:5]
	v_pk_mul_f32 v[2:3], v[12:13], v[2:3]
	s_nop 0
	v_cvt_pk_bf16_f32 v2, v2, v3
	v_cvt_pk_bf16_f32 v3, v4, v5
	global_store_dwordx2 v[20:21], v[2:3], off offset:224
	ds_read_b128 v[2:5], v160 offset:480
	s_waitcnt lgkmcnt(0)
	v_pk_mul_f32 v[2:3], v[6:7], v[2:3]
	v_pk_mul_f32 v[4:5], v[8:9], v[4:5]
	v_cvt_pk_bf16_f32 v2, v2, v3
	v_cvt_pk_bf16_f32 v3, v4, v5
	global_store_dwordx2 v[20:21], v[2:3], off offset:240
	s_branch .LBB0_1782

	.amdhsa_kernel _Z4mega6Params
		.amdhsa_group_segment_fixed_size 77840
		.amdhsa_private_segment_fixed_size 0
		.amdhsa_kernarg_size 496
		.amdhsa_user_sgpr_count 2
		.amdhsa_user_sgpr_dispatch_ptr 0
		.amdhsa_user_sgpr_queue_ptr 0
		.amdhsa_user_sgpr_kernarg_segment_ptr 1
		.amdhsa_user_sgpr_dispatch_id 0
		.amdhsa_user_sgpr_kernarg_preload_length 0
		.amdhsa_user_sgpr_kernarg_preload_offset 0
		.amdhsa_user_sgpr_private_segment_size 0
		.amdhsa_uses_dynamic_stack 0
		.amdhsa_enable_private_segment 0
		.amdhsa_system_sgpr_workgroup_id_x 1
		.amdhsa_system_sgpr_workgroup_id_y 0
		.amdhsa_system_sgpr_workgroup_id_z 0
		.amdhsa_system_sgpr_workgroup_info 0
		.amdhsa_system_vgpr_workitem_id 2
		.amdhsa_next_free_vgpr 256
		.amdhsa_next_free_sgpr 102
		.amdhsa_accum_offset 256
		.amdhsa_reserve_vcc 1
		.amdhsa_float_round_mode_32 0
		.amdhsa_float_round_mode_16_64 0
		.amdhsa_float_denorm_mode_32 3
		.amdhsa_float_denorm_mode_16_64 3
		.amdhsa_dx10_clamp 1
		.amdhsa_ieee_mode 1
		.amdhsa_fp16_overflow 0
		.amdhsa_tg_split 0
		.amdhsa_exception_fp_ieee_invalid_op 0
		.amdhsa_exception_fp_denorm_src 0
		.amdhsa_exception_fp_ieee_div_zero 0
		.amdhsa_exception_fp_ieee_overflow 0
		.amdhsa_exception_fp_ieee_underflow 0
		.amdhsa_exception_fp_ieee_inexact 0
		.amdhsa_exception_int_div_zero 0
	.end_amdhsa_kernel

amdhsa.kernels:
  - .agpr_count:     0
    .args:
      - .offset:         0
        .size:           240
        .value_kind:     by_value
      - .offset:         240
        .size:           4
        .value_kind:     hidden_block_count_x
      - .offset:         244
        .size:           4
        .value_kind:     hidden_block_count_y
      - .offset:         248
        .size:           4
        .value_kind:     hidden_block_count_z
      - .offset:         252
        .size:           2
        .value_kind:     hidden_group_size_x
      - .offset:         254
        .size:           2
        .value_kind:     hidden_group_size_y
      - .offset:         256
        .size:           2
        .value_kind:     hidden_group_size_z
      - .offset:         258
        .size:           2
        .value_kind:     hidden_remainder_x
      - .offset:         260
        .size:           2
        .value_kind:     hidden_remainder_y
      - .offset:         262
        .size:           2
        .value_kind:     hidden_remainder_z
      - .offset:         280
        .size:           8
        .value_kind:     hidden_global_offset_x
      - .offset:         288
        .size:           8
        .value_kind:     hidden_global_offset_y
      - .offset:         296
        .size:           8
        .value_kind:     hidden_global_offset_z
      - .offset:         304
        .size:           2
        .value_kind:     hidden_grid_dims
      - .offset:         328
        .size:           8
        .value_kind:     hidden_multigrid_sync_arg
    .group_segment_fixed_size: 77840
    .kernarg_segment_align: 8
    .kernarg_segment_size: 496
    .language:       OpenCL C
    .language_version:
      - 2
      - 0
    .max_flat_workgroup_size: 256
    .name:           _Z4mega6Params
    .private_segment_fixed_size: 0
    .sgpr_count:     108
    .sgpr_spill_count: 192
    .symbol:         _Z4mega6Params.kd
    .uniform_work_group_size: 1
    .uses_dynamic_stack: false
    .vgpr_count:     256
    .vgpr_spill_count: 0
    .wavefront_size: 64
